# gMLP item: a_v row blocks and the output part's ur/zr/bias loads issued together; out GEMM waves own 64 contiguous columns; row passes load the loop-invariant gain vectors once and their ladders use c
# speedup vs baseline: 1.0308x; 1.0059x over previous
.LBB0_264:
	s_or_b64 exec, exec, s[6:7]
	s_and_b32 s2, s24, 7
	s_or_b32 s6, s2, s0
	s_ashr_i32 s7, s6, 31
	v_readlane_b32 s72, v252, 9
	s_lshl_b64 s[8:9], s[6:7], 16
	v_readlane_b32 s82, v252, 19
	v_readlane_b32 s83, v252, 20
	s_add_u32 s8, s82, s8
	v_ashrrev_i32_e32 v1, 31, v0
	s_addc_u32 s9, s83, s9
	s_waitcnt vmcnt(3)
	v_lshl_add_u64 v[136:137], v[0:1], 2, s[8:9]
	v_mov_b32_e32 v138, 0x2000
	v_mov_b32_e32 v139, 0
	global_load_dwordx4 v[104:107], v[136:137], off
	v_lshl_add_u64 v[136:137], v[136:137], 0, v[138:139]
	global_load_dwordx4 v[108:111], v[136:137], off
	v_lshl_add_u64 v[136:137], v[136:137], 0, v[138:139]
	global_load_dwordx4 v[112:115], v[136:137], off
	v_lshl_add_u64 v[136:137], v[136:137], 0, v[138:139]
	global_load_dwordx4 v[116:119], v[136:137], off
	v_lshl_add_u64 v[136:137], v[136:137], 0, v[138:139]
	global_load_dwordx4 v[120:123], v[136:137], off
	v_lshl_add_u64 v[136:137], v[136:137], 0, v[138:139]
	global_load_dwordx4 v[124:127], v[136:137], off
	v_lshl_add_u64 v[136:137], v[136:137], 0, v[138:139]
	global_load_dwordx4 v[128:131], v[136:137], off
	v_lshl_add_u64 v[136:137], v[136:137], 0, v[138:139]
	global_load_dwordx4 v[132:135], v[136:137], off
	s_waitcnt vmcnt(10)
	v_lshlrev_b32_e32 v8, 3, v68
	v_and_b32_e32 v2, 0xf8, v8
	v_add_u32_e32 v2, 0, v2
	v_ashrrev_i32_e32 v3, 7, v0
	s_movk_i32 s3, 0x110
	v_ashrrev_i32_e32 v20, 4, v68
	v_lshlrev_b32_e32 v26, 4, v68
	v_and_b32_e32 v69, 0x78, v8
	s_lshl_b32 s2, s2, 8
	v_mov_b64_e32 v[66:67], s[54:55]
	s_mov_b64 s[60:61], 0x1000
	v_bfe_u32 v24, v8, 5, 2
	v_and_b32_e32 v21, 48, v20
	v_add_u32_e32 v29, 32, v20
	v_and_b32_e32 v25, 63, v68
	v_bfe_u32 v102, v68, 5, 1
	v_readlane_b32 s73, v252, 10
	v_readlane_b32 s74, v252, 11
	v_readlane_b32 s75, v252, 12
	v_readlane_b32 s76, v252, 13
	v_readlane_b32 s77, v252, 14
	v_readlane_b32 s78, v252, 15
	v_readlane_b32 s79, v252, 16
	v_readlane_b32 s80, v252, 17
	v_readlane_b32 s81, v252, 18
	v_readlane_b32 s84, v252, 21
	v_readlane_b32 s85, v252, 22
	v_readlane_b32 s86, v252, 23
	v_readlane_b32 s87, v252, 24
	s_waitcnt vmcnt(7)
	v_cvt_pk_bf16_f32 v4, v104, v105
	v_cvt_pk_bf16_f32 v5, v106, v107
	v_mad_u64_u32 v[6:7], s[26:27], v3, s3, v[2:3]
	ds_write_b64 v6, v[4:5]
	s_waitcnt vmcnt(6)
	v_cvt_pk_bf16_f32 v4, v108, v109
	v_cvt_pk_bf16_f32 v5, v110, v111
	ds_write_b64 v6, v[4:5] offset:4352
	s_waitcnt vmcnt(5)
	v_cvt_pk_bf16_f32 v4, v112, v113
	v_cvt_pk_bf16_f32 v5, v114, v115
	ds_write_b64 v6, v[4:5] offset:8704
	s_waitcnt vmcnt(4)
	v_cvt_pk_bf16_f32 v4, v116, v117
	v_cvt_pk_bf16_f32 v5, v118, v119
	ds_write_b64 v6, v[4:5] offset:13056
	s_waitcnt vmcnt(3)
	v_cvt_pk_bf16_f32 v4, v120, v121
	v_cvt_pk_bf16_f32 v5, v122, v123
	ds_write_b64 v6, v[4:5] offset:17408
	s_waitcnt vmcnt(2)
	v_cvt_pk_bf16_f32 v4, v124, v125
	v_cvt_pk_bf16_f32 v5, v126, v127
	ds_write_b64 v6, v[4:5] offset:21760
	s_waitcnt vmcnt(1)
	v_cvt_pk_bf16_f32 v4, v128, v129
	v_cvt_pk_bf16_f32 v5, v130, v131
	ds_write_b64 v6, v[4:5] offset:26112
	s_waitcnt vmcnt(0)
	v_cvt_pk_bf16_f32 v4, v132, v133
	v_cvt_pk_bf16_f32 v5, v134, v135
	ds_write_b64 v6, v[4:5] offset:30464
	s_add_i32 s3, 0, 0x18800
	v_lshrrev_b32_e32 v0, 1, v20
	v_and_b32_e32 v1, 3, v20
	v_and_or_b32 v0, v0, 4, v1
	v_and_b32_e32 v1, 48, v26
	v_lshl_or_b32 v28, v0, 6, v1
	v_add_u32_e32 v0, s25, v20
	v_or_b32_e32 v2, s2, v69
	v_mad_i64_i32 v[0:1], s[8:9], v0, s69, v[66:67]
	v_lshl_add_u64 v[18:19], v[0:1], 0, s[60:61]
	v_lshlrev_b32_e32 v64, 1, v2
	v_lshl_add_u64 v[0:1], v[18:19], 0, v[64:65]
	s_waitcnt lgkmcnt(0)
	s_barrier
	global_load_dwordx4 v[30:33], v[0:1], off nt
	v_mov_b32_e32 v138, 0x141000
	v_mov_b32_e32 v139, 0
	v_lshl_add_u64 v[136:137], v[0:1], 0, v[138:139]
	global_load_dwordx4 v[104:107], v[136:137], off nt
	global_load_dwordx4 v[120:123], v[136:137], off offset:256 nt
	v_lshl_add_u64 v[136:137], v[136:137], 0, v[138:139]
	global_load_dwordx4 v[108:111], v[136:137], off nt
	global_load_dwordx4 v[124:127], v[136:137], off offset:256 nt
	v_lshl_add_u64 v[136:137], v[136:137], 0, v[138:139]
	global_load_dwordx4 v[112:115], v[136:137], off nt
	global_load_dwordx4 v[128:131], v[136:137], off offset:256 nt
	global_load_dwordx4 v[116:119], v[0:1], off offset:256 nt
	v_lshlrev_b32_e32 v0, 2, v20
	s_add_i32 s8, 0, 0x18a00
	v_add_u32_e32 v36, s3, v0
	v_add_u32_e32 v37, s8, v0
	v_lshlrev_b32_e32 v27, 2, v2
	ds_read_b32 v16, v36
	ds_read_b32 v22, v37
	global_load_dwordx4 v[0:3], v27, s[56:57]
	global_load_dwordx4 v[4:7], v27, s[58:59]
	s_waitcnt vmcnt(2)
	v_lshlrev_b32_e32 v8, 16, v30
	v_and_b32_e32 v9, 0xffff0000, v30
	s_waitcnt lgkmcnt(1)
	v_pk_add_f32 v[8:9], v[8:9], v[16:17] op_sel_hi:[1,0] neg_lo:[0,1] neg_hi:[0,1]
	v_lshlrev_b32_e32 v30, 16, v31
	s_waitcnt lgkmcnt(0)
	v_pk_mul_f32 v[8:9], v[22:23], v[8:9] op_sel_hi:[0,1]
	v_and_b32_e32 v31, 0xffff0000, v31
	v_pk_add_f32 v[30:31], v[30:31], v[16:17] op_sel_hi:[1,0] neg_lo:[0,1] neg_hi:[0,1]
	s_waitcnt vmcnt(0)
	v_pk_fma_f32 v[34:35], v[0:1], v[8:9], v[4:5]
	v_lshlrev_b32_e32 v8, 16, v32
	v_and_b32_e32 v9, 0xffff0000, v32
	v_pk_add_f32 v[8:9], v[8:9], v[16:17] op_sel_hi:[1,0] neg_lo:[0,1] neg_hi:[0,1]
	v_lshlrev_b32_e32 v32, 16, v33
	v_pk_mul_f32 v[38:39], v[22:23], v[8:9] op_sel_hi:[0,1]
	global_load_dwordx4 v[8:11], v27, s[56:57] offset:16
	global_load_dwordx4 v[12:15], v27, s[58:59] offset:16
	v_and_b32_e32 v33, 0xffff0000, v33
	v_pk_add_f32 v[16:17], v[32:33], v[16:17] op_sel_hi:[1,0] neg_lo:[0,1] neg_hi:[0,1]
	v_pk_mul_f32 v[30:31], v[22:23], v[30:31] op_sel_hi:[0,1]
	v_pk_mul_f32 v[16:17], v[22:23], v[16:17] op_sel_hi:[0,1]
	v_pk_fma_f32 v[30:31], v[2:3], v[30:31], v[6:7]
	s_waitcnt vmcnt(0)
	v_pk_fma_f32 v[40:41], v[8:9], v[38:39], v[12:13]
	v_pk_fma_f32 v[16:17], v[10:11], v[16:17], v[14:15]
	v_cvt_pk_bf16_f32 v40, v40, v41
	v_cvt_pk_bf16_f32 v41, v16, v17
	v_lshlrev_b32_e32 v17, 1, v20
	v_and_or_b32 v17, v17, 8, v21
	v_lshrrev_b32_e32 v17, 1, v17
	v_lshlrev_b32_e32 v16, 8, v20
	v_or_b32_e32 v17, v17, v24
	v_and_b32_e32 v16, 0xffffc000, v16
	v_lshl_or_b32 v17, v17, 9, v28
	v_cvt_pk_bf16_f32 v38, v34, v35
	v_cvt_pk_bf16_f32 v39, v30, v31
	v_add3_u32 v16, 0, v16, v17
	v_add_u32_e32 v32, 0x8800, v16
	ds_write_b128 v16, v[38:41] offset:34816
	v_add_u32_e32 v16, s25, v29
	v_mad_i64_i32 v[16:17], s[26:27], v16, s69, v[66:67]
	v_lshl_add_u64 v[16:17], v[16:17], 0, s[60:61]
	v_lshl_add_u64 v[22:23], v[16:17], 0, v[64:65]
	v_mov_b32_e32 v38, v104
	v_mov_b32_e32 v39, v105
	v_mov_b32_e32 v40, v106
	v_mov_b32_e32 v41, v107
	v_lshlrev_b32_e32 v23, 2, v29
	v_add_u32_e32 v33, s3, v23
	ds_read_b32 v22, v33
	v_add_u32_e32 v34, s8, v23
	ds_read_b32 v30, v34
	s_waitcnt vmcnt(0)
	v_lshlrev_b32_e32 v42, 16, v38
	v_and_b32_e32 v43, 0xffff0000, v38
	v_lshlrev_b32_e32 v38, 16, v39
	v_and_b32_e32 v39, 0xffff0000, v39
	s_waitcnt lgkmcnt(1)
	v_pk_add_f32 v[38:39], v[38:39], v[22:23] op_sel_hi:[1,0] neg_lo:[0,1] neg_hi:[0,1]
	v_lshlrev_b32_e32 v44, 16, v40
	s_waitcnt lgkmcnt(0)
	v_pk_mul_f32 v[38:39], v[30:31], v[38:39] op_sel_hi:[0,1]
	v_and_b32_e32 v45, 0xffff0000, v40
	v_pk_fma_f32 v[46:47], v[2:3], v[38:39], v[6:7]
	v_lshlrev_b32_e32 v38, 16, v41
	v_and_b32_e32 v39, 0xffff0000, v41
	v_pk_add_f32 v[42:43], v[42:43], v[22:23] op_sel_hi:[1,0] neg_lo:[0,1] neg_hi:[0,1]
	v_pk_add_f32 v[44:45], v[44:45], v[22:23] op_sel_hi:[1,0] neg_lo:[0,1] neg_hi:[0,1]
	v_pk_add_f32 v[22:23], v[38:39], v[22:23] op_sel_hi:[1,0] neg_lo:[0,1] neg_hi:[0,1]
	v_pk_mul_f32 v[42:43], v[30:31], v[42:43] op_sel_hi:[0,1]
	v_pk_mul_f32 v[22:23], v[30:31], v[22:23] op_sel_hi:[0,1]
	v_pk_fma_f32 v[22:23], v[10:11], v[22:23], v[14:15]
	v_pk_mul_f32 v[44:45], v[30:31], v[44:45] op_sel_hi:[0,1]
	v_cvt_pk_bf16_f32 v41, v22, v23
	v_lshlrev_b32_e32 v22, 8, v29
	v_and_b32_e32 v23, 48, v29
	v_lshlrev_b32_e32 v29, 1, v29
	v_and_or_b32 v23, v29, 8, v23
	v_lshrrev_b32_e32 v23, 1, v23
	v_or_b32_e32 v23, v23, v24
	v_pk_fma_f32 v[42:43], v[0:1], v[42:43], v[4:5]
	v_pk_fma_f32 v[44:45], v[8:9], v[44:45], v[12:13]
	v_and_b32_e32 v22, 0xffffc000, v22
	v_lshl_or_b32 v23, v23, 9, v28
	v_cvt_pk_bf16_f32 v38, v42, v43
	v_cvt_pk_bf16_f32 v39, v46, v47
	v_cvt_pk_bf16_f32 v40, v44, v45
	v_add3_u32 v22, 0, v22, v23
	v_add_u32_e32 v29, 64, v20
	v_add_u32_e32 v35, 0x8800, v22
	ds_write_b128 v22, v[38:41] offset:34816
	v_add_u32_e32 v22, s25, v29
	v_mad_i64_i32 v[22:23], s[26:27], v22, s69, v[66:67]
	v_lshl_add_u64 v[22:23], v[22:23], 0, s[60:61]
	v_lshl_add_u64 v[30:31], v[22:23], 0, v[64:65]
	v_mov_b32_e32 v40, v108
	v_mov_b32_e32 v41, v109
	v_mov_b32_e32 v42, v110
	v_mov_b32_e32 v43, v111
	v_lshlrev_b32_e32 v31, 2, v29
	v_add_u32_e32 v38, s3, v31
	ds_read_b32 v30, v38
	v_add_u32_e32 v39, s8, v31
	ds_read_b32 v44, v39
	s_waitcnt vmcnt(0)
	v_lshlrev_b32_e32 v46, 16, v40
	v_and_b32_e32 v47, 0xffff0000, v40
	v_lshlrev_b32_e32 v40, 16, v41
	v_and_b32_e32 v41, 0xffff0000, v41
	s_waitcnt lgkmcnt(1)
	v_pk_add_f32 v[40:41], v[40:41], v[30:31] op_sel_hi:[1,0] neg_lo:[0,1] neg_hi:[0,1]
	v_lshlrev_b32_e32 v48, 16, v42
	s_waitcnt lgkmcnt(0)
	v_pk_mul_f32 v[40:41], v[44:45], v[40:41] op_sel_hi:[0,1]
	v_and_b32_e32 v49, 0xffff0000, v42
	v_pk_fma_f32 v[50:51], v[2:3], v[40:41], v[6:7]
	v_lshlrev_b32_e32 v40, 16, v43
	v_and_b32_e32 v41, 0xffff0000, v43
	v_pk_add_f32 v[46:47], v[46:47], v[30:31] op_sel_hi:[1,0] neg_lo:[0,1] neg_hi:[0,1]
	v_pk_add_f32 v[48:49], v[48:49], v[30:31] op_sel_hi:[1,0] neg_lo:[0,1] neg_hi:[0,1]
	v_pk_add_f32 v[30:31], v[40:41], v[30:31] op_sel_hi:[1,0] neg_lo:[0,1] neg_hi:[0,1]
	v_pk_mul_f32 v[46:47], v[44:45], v[46:47] op_sel_hi:[0,1]
	v_pk_mul_f32 v[30:31], v[44:45], v[30:31] op_sel_hi:[0,1]
	v_pk_fma_f32 v[30:31], v[10:11], v[30:31], v[14:15]
	v_pk_mul_f32 v[48:49], v[44:45], v[48:49] op_sel_hi:[0,1]
	v_cvt_pk_bf16_f32 v43, v30, v31
	v_lshlrev_b32_e32 v30, 8, v29
	v_lshlrev_b32_e32 v29, 1, v29
	v_and_or_b32 v21, v29, 8, v21
	v_lshrrev_b32_e32 v21, 1, v21
	v_or_b32_e32 v21, v21, v24
	v_pk_fma_f32 v[46:47], v[0:1], v[46:47], v[4:5]
	v_pk_fma_f32 v[48:49], v[8:9], v[48:49], v[12:13]
	v_and_b32_e32 v30, 0xffffc000, v30
	v_lshl_or_b32 v21, v21, 9, v28
	v_add_u32_e32 v45, 0x60, v20
	v_cvt_pk_bf16_f32 v40, v46, v47
	v_cvt_pk_bf16_f32 v41, v50, v51
	v_cvt_pk_bf16_f32 v42, v48, v49
	v_add3_u32 v21, 0, v30, v21
	v_add_u32_e32 v20, s25, v45
	v_add_u32_e32 v31, 0x8800, v21
	ds_write_b128 v21, v[40:43] offset:34816
	v_mad_i64_i32 v[20:21], s[26:27], v20, s69, v[66:67]
	v_lshl_add_u64 v[20:21], v[20:21], 0, s[60:61]
	v_lshl_add_u64 v[40:41], v[20:21], 0, v[64:65]
	v_mov_b32_e32 v40, v112
	v_mov_b32_e32 v41, v113
	v_mov_b32_e32 v42, v114
	v_mov_b32_e32 v43, v115
	v_lshlrev_b32_e32 v30, 2, v45
	v_add_u32_e32 v29, s3, v30
	ds_read_b32 v44, v29
	v_add_u32_e32 v30, s8, v30
	ds_read_b32 v46, v30
	v_or_b32_e32 v64, 0x100, v64
	s_waitcnt vmcnt(0)
	v_lshlrev_b32_e32 v48, 16, v40
	v_and_b32_e32 v49, 0xffff0000, v40
	s_waitcnt lgkmcnt(1)
	v_pk_add_f32 v[48:49], v[48:49], v[44:45] op_sel_hi:[1,0] neg_lo:[0,1] neg_hi:[0,1]
	s_waitcnt lgkmcnt(0)
	v_pk_mul_f32 v[48:49], v[46:47], v[48:49] op_sel_hi:[0,1]
	v_pk_fma_f32 v[0:1], v[0:1], v[48:49], v[4:5]
	v_lshlrev_b32_e32 v4, 16, v42
	v_and_b32_e32 v5, 0xffff0000, v42
	v_pk_add_f32 v[4:5], v[4:5], v[44:45] op_sel_hi:[1,0] neg_lo:[0,1] neg_hi:[0,1]
	v_cvt_pk_bf16_f32 v0, v0, v1
	v_pk_mul_f32 v[4:5], v[46:47], v[4:5] op_sel_hi:[0,1]
	v_pk_fma_f32 v[4:5], v[8:9], v[4:5], v[12:13]
	v_lshlrev_b32_e32 v8, 16, v41
	v_and_b32_e32 v9, 0xffff0000, v41
	v_pk_add_f32 v[8:9], v[8:9], v[44:45] op_sel_hi:[1,0] neg_lo:[0,1] neg_hi:[0,1]
	s_nop 0
	v_pk_mul_f32 v[8:9], v[46:47], v[8:9] op_sel_hi:[0,1]
	v_pk_fma_f32 v[2:3], v[2:3], v[8:9], v[6:7]
	v_lshlrev_b32_e32 v6, 16, v43
	v_and_b32_e32 v7, 0xffff0000, v43
	v_pk_add_f32 v[6:7], v[6:7], v[44:45] op_sel_hi:[1,0] neg_lo:[0,1] neg_hi:[0,1]
	v_cvt_pk_bf16_f32 v1, v2, v3
	v_pk_mul_f32 v[6:7], v[46:47], v[6:7] op_sel_hi:[0,1]
	v_pk_fma_f32 v[6:7], v[10:11], v[6:7], v[14:15]
	v_cvt_pk_bf16_f32 v2, v4, v5
	v_cvt_pk_bf16_f32 v3, v6, v7
	v_and_b32_e32 v5, 48, v45
	v_lshlrev_b32_e32 v6, 1, v45
	v_and_or_b32 v5, v6, 8, v5
	v_lshrrev_b32_e32 v5, 1, v5
	v_lshlrev_b32_e32 v4, 8, v45
	v_or_b32_e32 v5, v5, v24
	v_and_b32_e32 v4, 0xffffc000, v4
	v_lshl_or_b32 v5, v5, 9, v28
	v_add3_u32 v4, 0, v4, v5
	ds_write_b128 v4, v[0:3] offset:34816
	v_lshl_add_u64 v[0:1], v[18:19], 0, v[64:65]
	v_mov_b32_e32 v12, v116
	v_mov_b32_e32 v13, v117
	v_mov_b32_e32 v14, v118
	v_mov_b32_e32 v15, v119
	v_add_u32_e32 v28, 0x8800, v4
	ds_read_b32 v18, v36
	ds_read_b32 v24, v37
	global_load_dwordx4 v[0:3], v27, s[56:57] offset:512
	global_load_dwordx4 v[8:11], v27, s[56:57] offset:528
	global_load_dwordx4 v[4:7], v27, s[58:59] offset:512
	global_load_dwordx4 v[40:43], v27, s[58:59] offset:528
	s_waitcnt vmcnt(4)
	v_lshlrev_b32_e32 v36, 16, v12
	v_and_b32_e32 v37, 0xffff0000, v12
	v_lshlrev_b32_e32 v12, 16, v13
	v_and_b32_e32 v13, 0xffff0000, v13
	s_waitcnt lgkmcnt(1)
	v_pk_add_f32 v[12:13], v[12:13], v[18:19] op_sel_hi:[1,0] neg_lo:[0,1] neg_hi:[0,1]
	v_lshlrev_b32_e32 v44, 16, v14
	s_waitcnt lgkmcnt(0)
	v_pk_mul_f32 v[12:13], v[24:25], v[12:13] op_sel_hi:[0,1]
	v_and_b32_e32 v45, 0xffff0000, v14
	s_waitcnt vmcnt(1)
	v_pk_fma_f32 v[46:47], v[2:3], v[12:13], v[6:7]
	v_lshlrev_b32_e32 v12, 16, v15
	v_and_b32_e32 v13, 0xffff0000, v15
	v_pk_add_f32 v[36:37], v[36:37], v[18:19] op_sel_hi:[1,0] neg_lo:[0,1] neg_hi:[0,1]
	v_pk_add_f32 v[44:45], v[44:45], v[18:19] op_sel_hi:[1,0] neg_lo:[0,1] neg_hi:[0,1]
	v_pk_add_f32 v[12:13], v[12:13], v[18:19] op_sel_hi:[1,0] neg_lo:[0,1] neg_hi:[0,1]
	v_pk_mul_f32 v[36:37], v[24:25], v[36:37] op_sel_hi:[0,1]
	v_pk_mul_f32 v[44:45], v[24:25], v[44:45] op_sel_hi:[0,1]
	v_pk_mul_f32 v[12:13], v[24:25], v[12:13] op_sel_hi:[0,1]
	v_pk_fma_f32 v[36:37], v[0:1], v[36:37], v[4:5]
	s_waitcnt vmcnt(0)
	v_pk_fma_f32 v[44:45], v[8:9], v[44:45], v[40:41]
	v_pk_fma_f32 v[18:19], v[10:11], v[12:13], v[42:43]
	v_cvt_pk_bf16_f32 v12, v36, v37
	v_cvt_pk_bf16_f32 v13, v46, v47
	v_cvt_pk_bf16_f32 v14, v44, v45
	v_cvt_pk_bf16_f32 v15, v18, v19
	ds_write_b128 v32, v[12:15] offset:32768
	v_lshl_add_u64 v[12:13], v[16:17], 0, v[64:65]
	v_mov_b32_e32 v12, v120
	v_mov_b32_e32 v13, v121
	v_mov_b32_e32 v14, v122
	v_mov_b32_e32 v15, v123
	ds_read_b32 v16, v33
	ds_read_b32 v18, v34
	s_waitcnt vmcnt(0)
	v_lshlrev_b32_e32 v36, 16, v14
	v_and_b32_e32 v37, 0xffff0000, v14
	s_waitcnt lgkmcnt(1)
	v_pk_add_f32 v[36:37], v[36:37], v[16:17] op_sel_hi:[1,0] neg_lo:[0,1] neg_hi:[0,1]
	v_lshlrev_b32_e32 v32, 16, v12
	s_waitcnt lgkmcnt(0)
	v_pk_mul_f32 v[36:37], v[18:19], v[36:37] op_sel_hi:[0,1]
	v_pk_fma_f32 v[36:37], v[8:9], v[36:37], v[40:41]
	v_lshlrev_b32_e32 v8, 16, v13
	v_and_b32_e32 v9, 0xffff0000, v13
	v_pk_add_f32 v[8:9], v[8:9], v[16:17] op_sel_hi:[1,0] neg_lo:[0,1] neg_hi:[0,1]
	v_and_b32_e32 v33, 0xffff0000, v12
	v_pk_mul_f32 v[8:9], v[18:19], v[8:9] op_sel_hi:[0,1]
	v_pk_fma_f32 v[12:13], v[2:3], v[8:9], v[6:7]
	v_lshlrev_b32_e32 v8, 16, v15
	v_and_b32_e32 v9, 0xffff0000, v15
	v_pk_add_f32 v[32:33], v[32:33], v[16:17] op_sel_hi:[1,0] neg_lo:[0,1] neg_hi:[0,1]
	v_pk_add_f32 v[8:9], v[8:9], v[16:17] op_sel_hi:[1,0] neg_lo:[0,1] neg_hi:[0,1]
	v_pk_mul_f32 v[32:33], v[18:19], v[32:33] op_sel_hi:[0,1]
	v_pk_mul_f32 v[8:9], v[18:19], v[8:9] op_sel_hi:[0,1]
	v_pk_fma_f32 v[32:33], v[0:1], v[32:33], v[4:5]
	v_pk_fma_f32 v[14:15], v[10:11], v[8:9], v[42:43]
	v_cvt_pk_bf16_f32 v8, v32, v33
	v_cvt_pk_bf16_f32 v9, v12, v13
	v_cvt_pk_bf16_f32 v10, v36, v37
	v_cvt_pk_bf16_f32 v11, v14, v15
	ds_write_b128 v35, v[8:11] offset:32768
	v_lshl_add_u64 v[8:9], v[22:23], 0, v[64:65]
	v_mov_b32_e32 v12, v124
	v_mov_b32_e32 v13, v125
	v_mov_b32_e32 v14, v126
	v_mov_b32_e32 v15, v127
	ds_read_b32 v22, v38
	ds_read_b32 v24, v39
	global_load_dwordx4 v[8:11], v27, s[56:57] offset:528
	global_load_dwordx4 v[16:19], v27, s[58:59] offset:528
	s_waitcnt vmcnt(2)
	v_lshlrev_b32_e32 v32, 16, v12
	v_and_b32_e32 v33, 0xffff0000, v12
	v_lshlrev_b32_e32 v12, 16, v13
	v_and_b32_e32 v13, 0xffff0000, v13
	s_waitcnt lgkmcnt(1)
	v_pk_add_f32 v[12:13], v[12:13], v[22:23] op_sel_hi:[1,0] neg_lo:[0,1] neg_hi:[0,1]
	v_lshlrev_b32_e32 v34, 16, v14
	s_waitcnt lgkmcnt(0)
	v_pk_mul_f32 v[12:13], v[24:25], v[12:13] op_sel_hi:[0,1]
	v_and_b32_e32 v35, 0xffff0000, v14
	v_pk_fma_f32 v[36:37], v[2:3], v[12:13], v[6:7]
	v_lshlrev_b32_e32 v12, 16, v15
	v_and_b32_e32 v13, 0xffff0000, v15
	v_pk_add_f32 v[32:33], v[32:33], v[22:23] op_sel_hi:[1,0] neg_lo:[0,1] neg_hi:[0,1]
	v_pk_add_f32 v[34:35], v[34:35], v[22:23] op_sel_hi:[1,0] neg_lo:[0,1] neg_hi:[0,1]
	v_pk_add_f32 v[12:13], v[12:13], v[22:23] op_sel_hi:[1,0] neg_lo:[0,1] neg_hi:[0,1]
	v_pk_mul_f32 v[32:33], v[24:25], v[32:33] op_sel_hi:[0,1]
	v_pk_mul_f32 v[34:35], v[24:25], v[34:35] op_sel_hi:[0,1]
	v_pk_mul_f32 v[12:13], v[24:25], v[12:13] op_sel_hi:[0,1]
	v_pk_fma_f32 v[32:33], v[0:1], v[32:33], v[4:5]
	s_waitcnt vmcnt(0)
	v_pk_fma_f32 v[34:35], v[8:9], v[34:35], v[16:17]
	v_pk_fma_f32 v[22:23], v[10:11], v[12:13], v[18:19]
	v_cvt_pk_bf16_f32 v12, v32, v33
	v_cvt_pk_bf16_f32 v13, v36, v37
	v_cvt_pk_bf16_f32 v14, v34, v35
	v_cvt_pk_bf16_f32 v15, v22, v23
	ds_write_b128 v31, v[12:15] offset:32768
	v_lshl_add_u64 v[12:13], v[20:21], 0, v[64:65]
	v_mov_b32_e32 v12, v128
	v_mov_b32_e32 v13, v129
	v_mov_b32_e32 v14, v130
	v_mov_b32_e32 v15, v131
	ds_read_b32 v20, v29
	ds_read_b32 v22, v30
	v_and_b32_e32 v64, 31, v68
	s_waitcnt vmcnt(0)
	v_lshlrev_b32_e32 v30, 16, v12
	v_and_b32_e32 v31, 0xffff0000, v12
	s_waitcnt lgkmcnt(1)
	v_pk_add_f32 v[30:31], v[30:31], v[20:21] op_sel_hi:[1,0] neg_lo:[0,1] neg_hi:[0,1]
	s_waitcnt lgkmcnt(0)
	v_pk_mul_f32 v[30:31], v[22:23], v[30:31] op_sel_hi:[0,1]
	v_pk_fma_f32 v[0:1], v[0:1], v[30:31], v[4:5]
	v_lshlrev_b32_e32 v4, 16, v14
	v_and_b32_e32 v5, 0xffff0000, v14
	v_pk_add_f32 v[4:5], v[4:5], v[20:21] op_sel_hi:[1,0] neg_lo:[0,1] neg_hi:[0,1]
	v_cvt_pk_bf16_f32 v0, v0, v1
	v_pk_mul_f32 v[4:5], v[22:23], v[4:5] op_sel_hi:[0,1]
	v_pk_fma_f32 v[4:5], v[8:9], v[4:5], v[16:17]
	v_lshlrev_b32_e32 v8, 16, v13
	v_and_b32_e32 v9, 0xffff0000, v13
	v_pk_add_f32 v[8:9], v[8:9], v[20:21] op_sel_hi:[1,0] neg_lo:[0,1] neg_hi:[0,1]
	s_nop 0
	v_pk_mul_f32 v[8:9], v[22:23], v[8:9] op_sel_hi:[0,1]
	v_pk_fma_f32 v[2:3], v[2:3], v[8:9], v[6:7]
	v_lshlrev_b32_e32 v6, 16, v15
	v_and_b32_e32 v7, 0xffff0000, v15
	v_pk_add_f32 v[6:7], v[6:7], v[20:21] op_sel_hi:[1,0] neg_lo:[0,1] neg_hi:[0,1]
	v_cvt_pk_bf16_f32 v1, v2, v3
	v_pk_mul_f32 v[6:7], v[22:23], v[6:7] op_sel_hi:[0,1]
	v_pk_fma_f32 v[6:7], v[10:11], v[6:7], v[18:19]
	v_cvt_pk_bf16_f32 v2, v4, v5
	v_cvt_pk_bf16_f32 v3, v6, v7
	ds_write_b128 v28, v[0:3] offset:32768
	v_or_b32_e32 v0, s10, v64
	v_lshlrev_b32_e32 v2, 3, v25
	v_and_b32_e32 v3, 0xc0, v26
	v_lshlrev_b32_e32 v4, 1, v68
	v_mul_u32_u24_e32 v0, 0x110, v0
	v_lshlrev_b32_e32 v1, 4, v102
	v_and_or_b32 v3, v2, 24, v3
	v_and_b32_e32 v4, 32, v4
	v_and_b32_e32 v2, 0x100, v2
	v_or3_b32 v94, v3, v4, v2
	v_add3_u32 v95, 0, v0, v1
	s_waitcnt lgkmcnt(0)
	s_barrier
	ds_read_b128 v[48:51], v95
	ds_read_b128 v[70:73], v95 offset:32
	ds_read_b128 v[74:77], v95 offset:64
	ds_read_b128 v[78:81], v95 offset:96
	v_add_u32_e32 v96, s11, v94
	ds_read_b64_tr_b16 v[0:1], v96 offset:0
	ds_read_b64_tr_b16 v[2:3], v96 offset:0x800
	ds_read_b64_tr_b16 v[16:17], v96 offset:0x1000
	ds_read_b64_tr_b16 v[18:19], v96 offset:0x1800
	ds_read_b64_tr_b16 v[20:21], v96 offset:0x2000
	ds_read_b64_tr_b16 v[22:23], v96 offset:0x2800
	ds_read_b64_tr_b16 v[24:25], v96 offset:0x3000
	ds_read_b64_tr_b16 v[26:27], v96 offset:0x3800
	s_waitcnt lgkmcnt(0)
	s_waitcnt lgkmcnt(3)
	v_mfma_f32_32x32x16_bf16 v[0:15], v[48:51], v[0:3], 0
	s_waitcnt lgkmcnt(2)
	v_mfma_f32_32x32x16_bf16 v[0:15], v[70:73], v[16:19], v[0:15]
	ds_read_b64_tr_b16 v[16:17], v96 offset:0x200
	ds_read_b64_tr_b16 v[18:19], v96 offset:0xa00
	ds_read_b64_tr_b16 v[32:33], v96 offset:0x1200
	ds_read_b64_tr_b16 v[34:35], v96 offset:0x1a00
	ds_read_b64_tr_b16 v[36:37], v96 offset:0x2200
	ds_read_b64_tr_b16 v[38:39], v96 offset:0x2a00
	ds_read_b64_tr_b16 v[40:41], v96 offset:0x3200
	s_waitcnt lgkmcnt(1)
	v_mfma_f32_32x32x16_bf16 v[0:15], v[74:77], v[20:23], v[0:15]
	ds_read_b64_tr_b16 v[42:43], v96 offset:0x3a00
	s_waitcnt lgkmcnt(0)
	s_waitcnt lgkmcnt(0)
	v_mfma_f32_32x32x16_bf16 v[0:15], v[78:81], v[24:27], v[0:15]
	v_mfma_f32_32x32x16_bf16 v[16:31], v[48:51], v[16:19], 0
	v_mfma_f32_32x32x16_bf16 v[16:31], v[70:73], v[32:35], v[16:31]
	ds_read_b64_tr_b16 v[32:33], v96 offset:0x400
	ds_read_b64_tr_b16 v[34:35], v96 offset:0xc00
	ds_read_b64_tr_b16 v[52:53], v96 offset:0x1400
	ds_read_b64_tr_b16 v[54:55], v96 offset:0x1c00
	ds_read_b64_tr_b16 v[56:57], v96 offset:0x2400
	ds_read_b64_tr_b16 v[58:59], v96 offset:0x2c00
	ds_read_b64_tr_b16 v[60:61], v96 offset:0x3400
	v_mfma_f32_32x32x16_bf16 v[16:31], v[74:77], v[36:39], v[16:31]
	ds_read_b64_tr_b16 v[62:63], v96 offset:0x3c00
	s_waitcnt lgkmcnt(0)
	v_mfma_f32_32x32x16_bf16 v[16:31], v[78:81], v[40:43], v[16:31]
	v_mfma_f32_32x32x16_bf16 v[32:47], v[48:51], v[32:35], 0
	v_mfma_f32_32x32x16_bf16 v[32:47], v[70:73], v[52:55], v[32:47]
	ds_read_b64_tr_b16 v[52:53], v96 offset:0x600
	ds_read_b64_tr_b16 v[54:55], v96 offset:0xe00
	ds_read_b64_tr_b16 v[82:83], v96 offset:0x1600
	ds_read_b64_tr_b16 v[84:85], v96 offset:0x1e00
	ds_read_b64_tr_b16 v[86:87], v96 offset:0x2600
	ds_read_b64_tr_b16 v[88:89], v96 offset:0x2e00
	ds_read_b64_tr_b16 v[90:91], v96 offset:0x3600
	v_mfma_f32_32x32x16_bf16 v[32:47], v[74:77], v[56:59], v[32:47]
	ds_read_b64_tr_b16 v[92:93], v96 offset:0x3e00
	s_waitcnt lgkmcnt(0)
	v_mfma_f32_32x32x16_bf16 v[32:47], v[78:81], v[60:63], v[32:47]
	v_mfma_f32_32x32x16_bf16 v[48:63], v[48:51], v[52:55], 0
	v_add_u32_e32 v103, s12, v94
	v_mfma_f32_32x32x16_bf16 v[48:63], v[70:73], v[82:85], v[48:63]
	v_mfma_f32_32x32x16_bf16 v[48:63], v[74:77], v[86:89], v[48:63]
	v_mfma_f32_32x32x16_bf16 v[48:63], v[78:81], v[90:93], v[48:63]
	ds_read_b128 v[70:73], v95 offset:128
	ds_read_b128 v[74:77], v95 offset:160
	ds_read_b128 v[78:81], v95 offset:192
	ds_read_b128 v[82:85], v95 offset:224
	ds_read_b64_tr_b16 v[86:87], v103 offset:0
	ds_read_b64_tr_b16 v[88:89], v103 offset:0x800
	ds_read_b64_tr_b16 v[90:91], v103 offset:0x1000
	ds_read_b64_tr_b16 v[92:93], v103 offset:0x1800
	ds_read_b64_tr_b16 v[94:95], v103 offset:0x2000
	ds_read_b64_tr_b16 v[96:97], v103 offset:0x2800
	ds_read_b64_tr_b16 v[98:99], v103 offset:0x3000
	ds_read_b64_tr_b16 v[100:101], v103 offset:0x3800
	s_waitcnt lgkmcnt(0)
	s_waitcnt lgkmcnt(3)
	v_mfma_f32_32x32x16_bf16 v[0:15], v[70:73], v[86:89], v[0:15]
	ds_read_b64_tr_b16 v[86:87], v103 offset:0x200
	ds_read_b64_tr_b16 v[88:89], v103 offset:0xa00
	s_waitcnt lgkmcnt(2)
	v_mfma_f32_32x32x16_bf16 v[0:15], v[74:77], v[90:93], v[0:15]
	ds_read_b64_tr_b16 v[90:91], v103 offset:0x1200
	ds_read_b64_tr_b16 v[92:93], v103 offset:0x1a00
	s_waitcnt lgkmcnt(1)
	v_mfma_f32_32x32x16_bf16 v[0:15], v[78:81], v[94:97], v[0:15]
	ds_read_b64_tr_b16 v[94:95], v103 offset:0x2200
	ds_read_b64_tr_b16 v[96:97], v103 offset:0x2a00
	s_waitcnt lgkmcnt(0)
	v_mfma_f32_32x32x16_bf16 v[0:15], v[82:85], v[98:101], v[0:15]
	ds_read_b64_tr_b16 v[98:99], v103 offset:0x3200
	ds_read_b64_tr_b16 v[100:101], v103 offset:0x3a00
	s_waitcnt lgkmcnt(0)
	v_mfma_f32_32x32x16_bf16 v[16:31], v[70:73], v[86:89], v[16:31]
	ds_read_b64_tr_b16 v[86:87], v103 offset:0x400
	ds_read_b64_tr_b16 v[88:89], v103 offset:0xc00
	v_mfma_f32_32x32x16_bf16 v[16:31], v[74:77], v[90:93], v[16:31]
	ds_read_b64_tr_b16 v[90:91], v103 offset:0x1400
	ds_read_b64_tr_b16 v[92:93], v103 offset:0x1c00
	v_mfma_f32_32x32x16_bf16 v[16:31], v[78:81], v[94:97], v[16:31]
	ds_read_b64_tr_b16 v[94:95], v103 offset:0x2400
	ds_read_b64_tr_b16 v[96:97], v103 offset:0x2c00
	v_mfma_f32_32x32x16_bf16 v[16:31], v[82:85], v[98:101], v[16:31]
	ds_read_b64_tr_b16 v[98:99], v103 offset:0x3400
	ds_read_b64_tr_b16 v[100:101], v103 offset:0x3c00
	s_waitcnt lgkmcnt(0)
	v_mfma_f32_32x32x16_bf16 v[32:47], v[70:73], v[86:89], v[32:47]
	ds_read_b64_tr_b16 v[86:87], v103 offset:0x600
	ds_read_b64_tr_b16 v[88:89], v103 offset:0xe00
	v_mfma_f32_32x32x16_bf16 v[32:47], v[74:77], v[90:93], v[32:47]
	ds_read_b64_tr_b16 v[90:91], v103 offset:0x1600
	ds_read_b64_tr_b16 v[92:93], v103 offset:0x1e00
	v_mfma_f32_32x32x16_bf16 v[32:47], v[78:81], v[94:97], v[32:47]
	ds_read_b64_tr_b16 v[94:95], v103 offset:0x2600
	ds_read_b64_tr_b16 v[96:97], v103 offset:0x2e00
	v_mfma_f32_32x32x16_bf16 v[32:47], v[82:85], v[98:101], v[32:47]
	ds_read_b64_tr_b16 v[98:99], v103 offset:0x3600
	ds_read_b64_tr_b16 v[100:101], v103 offset:0x3e00
	s_waitcnt lgkmcnt(0)
	v_mfma_f32_32x32x16_bf16 v[48:63], v[70:73], v[86:89], v[48:63]
	v_mul_u32_u24_e32 v70, 0x840, v102
	v_lshlrev_b32_e32 v64, 2, v64
	v_add3_u32 v64, s13, v70, v64
	s_barrier
	s_add_i32 s2, s2, s14
	v_mfma_f32_32x32x16_bf16 v[48:63], v[74:77], v[90:93], v[48:63]
	s_movk_i32 s8, 0x2000
	v_mfma_f32_32x32x16_bf16 v[48:63], v[78:81], v[94:97], v[48:63]
	v_mfma_f32_32x32x16_bf16 v[48:63], v[82:85], v[98:101], v[48:63]
	ds_write2_b32 v64, v0, v16 offset1:32
	s_nop 10
	ds_write2_b32 v64, v32, v48 offset0:64 offset1:96
	ds_write2_b32 v64, v1, v17 offset0:132 offset1:164
	ds_write2_b32 v64, v33, v49 offset0:196 offset1:228
	v_add_u32_e32 v0, 0x400, v64
	ds_write2_b32 v0, v2, v18 offset0:8 offset1:40
	ds_write2_b32 v0, v34, v50 offset0:72 offset1:104
	ds_write2_b32 v0, v3, v19 offset0:140 offset1:172
	ds_write2_b32 v0, v35, v51 offset0:204 offset1:236
	v_add_u32_e32 v0, 0x1000, v64
	ds_write2_b32 v0, v4, v20 offset0:32 offset1:64
	ds_write2_b32 v0, v36, v52 offset0:96 offset1:128
	ds_write2_b32 v0, v5, v21 offset0:164 offset1:196
	v_add_u32_e32 v0, 0x1200, v64
	ds_write2_b32 v0, v37, v53 offset0:100 offset1:132
	v_add_u32_e32 v0, 0x1400, v64
	ds_write2_b32 v0, v6, v22 offset0:40 offset1:72
	ds_write2_b32 v0, v38, v54 offset0:104 offset1:136
	ds_write2_b32 v0, v7, v23 offset0:172 offset1:204
	v_add_u32_e32 v0, 0x1600, v64
	ds_write2_b32 v0, v39, v55 offset0:108 offset1:140
	v_add_u32_e32 v0, 0x2000, v64
	ds_write2_b32 v0, v8, v24 offset0:64 offset1:96
	ds_write2_b32 v0, v40, v56 offset0:128 offset1:160
	ds_write2_b32 v0, v9, v25 offset0:196 offset1:228
	v_add_u32_e32 v0, 0x2400, v64
	ds_write2_b32 v0, v41, v57 offset0:4 offset1:36
	ds_write2_b32 v0, v10, v26 offset0:72 offset1:104
	ds_write2_b32 v0, v42, v58 offset0:136 offset1:168
	ds_write2_b32 v0, v11, v27 offset0:204 offset1:236
	v_add_u32_e32 v0, 0x2800, v64
	ds_write2_b32 v0, v43, v59 offset0:12 offset1:44
	v_add_u32_e32 v0, 0x3000, v64
	ds_write2_b32 v0, v12, v28 offset0:96 offset1:128
	ds_write2_b32 v0, v44, v60 offset0:160 offset1:192
	v_add_u32_e32 v0, 0x3200, v64
	ds_write2_b32 v0, v13, v29 offset0:100 offset1:132
	v_add_u32_e32 v0, 0x3400, v64
	ds_write2_b32 v0, v45, v61 offset0:36 offset1:68
	ds_write2_b32 v0, v14, v30 offset0:104 offset1:136
	ds_write2_b32 v0, v46, v62 offset0:168 offset1:200
	v_add_u32_e32 v0, 0x3600, v64
	ds_write2_b32 v0, v15, v31 offset0:108 offset1:140
	v_add_u32_e32 v0, 0x3800, v64
	v_bfe_u32 v23, v68, 4, 2
	ds_write2_b32 v0, v47, v63 offset0:44 offset1:76
	v_or_b32_e32 v0, s2, v69
	v_or_b32_e32 v22, s10, v23
	v_ashrrev_i32_e32 v1, 31, v0
	v_or_b32_e32 v20, s25, v22
	v_lshlrev_b32_e32 v2, 2, v69
	s_lshl_b64 s[2:3], s[6:7], 9
	v_lshlrev_b64 v[18:19], 1, v[0:1]
	v_mul_u32_u24_e32 v0, 0x210, v23
	v_mad_i64_i32 v[8:9], s[6:7], v20, s69, v[66:67]
	v_add3_u32 v24, s13, v2, v0
	v_lshl_add_u64 v[8:9], v[8:9], 0, v[18:19]
	s_add_u32 s6, s84, s2
	ds_read_b128 v[4:7], v24
	ds_read_b128 v[0:3], v24 offset:16
	global_load_dwordx4 v[12:15], v[8:9], off nt
	v_add_co_u32_e32 v8, vcc, s8, v8
	s_addc_u32 s7, s85, s3
	v_lshlrev_b32_e32 v22, 2, v22
	v_addc_co_u32_e32 v9, vcc, 0, v9, vcc
	global_load_dword v22, v22, s[6:7]
	v_ashrrev_i32_e32 v21, 31, v20
	global_load_dwordx4 v[8:11], v[8:9], off nt
	v_mov_b32_e32 v178, 0x2000
	v_mov_b32_e32 v179, 0
	v_add_lshl_u32 v175, v23, s10, 2
	v_or_b32_e32 v180, s15, v23
	v_or_b32_e32 v180, s25, v180
	v_mad_i64_i32 v[176:177], s[2:3], v180, s69, v[66:67]
	v_lshl_add_u64 v[176:177], v[176:177], 0, v[18:19]
	global_load_dwordx4 v[104:107], v[176:177], off nt
	v_lshl_add_u64 v[176:177], v[176:177], 0, v[178:179]
	global_load_dwordx4 v[108:111], v[176:177], off nt
	global_load_dword v168, v175, s[6:7] offset:16
	v_or_b32_e32 v180, s16, v23
	v_or_b32_e32 v180, s25, v180
	v_mad_i64_i32 v[176:177], s[2:3], v180, s69, v[66:67]
	v_lshl_add_u64 v[176:177], v[176:177], 0, v[18:19]
	global_load_dwordx4 v[112:115], v[176:177], off nt
	v_lshl_add_u64 v[176:177], v[176:177], 0, v[178:179]
	global_load_dwordx4 v[116:119], v[176:177], off nt
	global_load_dword v169, v175, s[6:7] offset:32
	v_or_b32_e32 v180, s17, v23
	v_or_b32_e32 v180, s25, v180
	v_mad_i64_i32 v[176:177], s[2:3], v180, s69, v[66:67]
	v_lshl_add_u64 v[176:177], v[176:177], 0, v[18:19]
	global_load_dwordx4 v[120:123], v[176:177], off nt
	v_lshl_add_u64 v[176:177], v[176:177], 0, v[178:179]
	global_load_dwordx4 v[124:127], v[176:177], off nt
	global_load_dword v170, v175, s[6:7] offset:48
	v_or_b32_e32 v180, s18, v23
	v_or_b32_e32 v180, s25, v180
	v_mad_i64_i32 v[176:177], s[2:3], v180, s69, v[66:67]
	v_lshl_add_u64 v[176:177], v[176:177], 0, v[18:19]
	global_load_dwordx4 v[128:131], v[176:177], off nt
	v_lshl_add_u64 v[176:177], v[176:177], 0, v[178:179]
	global_load_dwordx4 v[132:135], v[176:177], off nt
	global_load_dword v171, v175, s[6:7] offset:64
	v_or_b32_e32 v180, s19, v23
	v_or_b32_e32 v180, s25, v180
	v_mad_i64_i32 v[176:177], s[2:3], v180, s69, v[66:67]
	v_lshl_add_u64 v[176:177], v[176:177], 0, v[18:19]
	global_load_dwordx4 v[136:139], v[176:177], off nt
	v_lshl_add_u64 v[176:177], v[176:177], 0, v[178:179]
	global_load_dwordx4 v[140:143], v[176:177], off nt
	global_load_dword v172, v175, s[6:7] offset:80
	v_or_b32_e32 v180, s20, v23
	v_or_b32_e32 v180, s25, v180
	v_mad_i64_i32 v[176:177], s[2:3], v180, s69, v[66:67]
	v_lshl_add_u64 v[176:177], v[176:177], 0, v[18:19]
	global_load_dwordx4 v[152:155], v[176:177], off nt
	v_lshl_add_u64 v[176:177], v[176:177], 0, v[178:179]
	global_load_dwordx4 v[156:159], v[176:177], off nt
	global_load_dword v173, v175, s[6:7] offset:96
	v_or_b32_e32 v180, s21, v23
	v_or_b32_e32 v180, s25, v180
	v_mad_i64_i32 v[176:177], s[2:3], v180, s69, v[66:67]
	v_lshl_add_u64 v[176:177], v[176:177], 0, v[18:19]
	global_load_dwordx4 v[160:163], v[176:177], off nt
	v_lshl_add_u64 v[176:177], v[176:177], 0, v[178:179]
	global_load_dwordx4 v[164:167], v[176:177], off nt
	global_load_dword v174, v175, s[6:7] offset:112
	v_lshl_add_u64 v[16:17], s[52:53], 0, v[18:19]
	s_add_i32 s24, s24, s42
	s_add_i32 s22, s22, s23
	s_cmpk_gt_i32 s24, 0x3ff
	s_waitcnt vmcnt(2)
	v_lshlrev_b32_e32 v26, 16, v12
	v_and_b32_e32 v27, 0xffff0000, v12
	v_lshlrev_b32_e32 v12, 16, v13
	v_and_b32_e32 v13, 0xffff0000, v13
	s_waitcnt vmcnt(1) lgkmcnt(1)
	v_pk_add_f32 v[4:5], v[4:5], v[22:23] op_sel_hi:[1,0]
	v_pk_add_f32 v[6:7], v[6:7], v[22:23] op_sel_hi:[1,0]
	v_pk_mul_f32 v[4:5], v[4:5], v[26:27]
	s_waitcnt vmcnt(0)
	v_lshlrev_b32_e32 v26, 16, v8
	v_and_b32_e32 v27, 0xffff0000, v8
	v_pk_mul_f32 v[6:7], v[6:7], v[12:13]
	v_lshlrev_b32_e32 v8, 16, v9
	v_and_b32_e32 v9, 0xffff0000, v9
	v_pk_mul_f32 v[6:7], v[6:7], v[8:9]
	s_waitcnt lgkmcnt(0)
	v_pk_add_f32 v[0:1], v[0:1], v[22:23] op_sel_hi:[1,0]
	v_lshlrev_b32_e32 v8, 16, v14
	v_and_b32_e32 v9, 0xffff0000, v14
	v_pk_mul_f32 v[0:1], v[0:1], v[8:9]
	v_lshlrev_b32_e32 v8, 16, v10
	v_and_b32_e32 v9, 0xffff0000, v10
	v_pk_mul_f32 v[8:9], v[0:1], v[8:9]
	v_pk_add_f32 v[0:1], v[2:3], v[22:23] op_sel_hi:[1,0]
	v_lshlrev_b32_e32 v2, 16, v15
	v_and_b32_e32 v3, 0xffff0000, v15
	v_pk_mul_f32 v[4:5], v[4:5], v[26:27]
	v_pk_mul_f32 v[0:1], v[0:1], v[2:3]
	v_lshlrev_b32_e32 v2, 16, v11
	v_and_b32_e32 v3, 0xffff0000, v11
	v_pk_mul_f32 v[10:11], v[0:1], v[2:3]
	v_cvt_pk_bf16_f32 v0, v4, v5
	v_lshlrev_b64 v[4:5], 12, v[20:21]
	v_cvt_pk_bf16_f32 v1, v6, v7
	v_cvt_pk_bf16_f32 v2, v8, v9
	v_cvt_pk_bf16_f32 v3, v10, v11
	v_lshl_add_u64 v[4:5], v[16:17], 0, v[4:5]
	global_store_dwordx4 v[4:5], v[0:3], off nt
	ds_read_b128 v[2:5], v24 offset:2112
	ds_read_b128 v[6:9], v24 offset:2128
	v_or_b32_e32 v0, s15, v23
	v_or_b32_e32 v14, s25, v0
	v_mad_i64_i32 v[0:1], s[2:3], v14, s69, v[66:67]
	v_lshl_add_u64 v[0:1], v[0:1], 0, v[18:19]
	v_mov_b32_e32 v10, v104
	v_mov_b32_e32 v11, v105
	v_mov_b32_e32 v12, v106
	v_mov_b32_e32 v13, v107
	v_add_co_u32_e32 v0, vcc, s8, v0
	v_ashrrev_i32_e32 v15, 31, v14
	s_nop 0
	v_addc_co_u32_e32 v1, vcc, 0, v1, vcc
	v_mov_b32_e32 v26, v108
	v_mov_b32_e32 v27, v109
	v_mov_b32_e32 v28, v110
	v_mov_b32_e32 v29, v111
	v_add_lshl_u32 v0, v23, s10, 2
	v_mov_b32_e32 v20, v168
	v_or_b32_e32 v1, s16, v23
	v_lshlrev_b32_e32 v30, 16, v10
	v_and_b32_e32 v31, 0xffff0000, v10
	v_lshlrev_b32_e32 v10, 16, v11
	v_and_b32_e32 v11, 0xffff0000, v11
	s_waitcnt lgkmcnt(1)
	v_pk_add_f32 v[4:5], v[4:5], v[20:21] op_sel_hi:[1,0]
	s_nop 0
	v_pk_mul_f32 v[4:5], v[4:5], v[10:11]
	v_lshlrev_b32_e32 v10, 16, v27
	v_and_b32_e32 v11, 0xffff0000, v27
	v_pk_mul_f32 v[4:5], v[4:5], v[10:11]
	s_waitcnt lgkmcnt(0)
	v_pk_add_f32 v[6:7], v[6:7], v[20:21] op_sel_hi:[1,0]
	v_lshlrev_b32_e32 v10, 16, v12
	v_and_b32_e32 v11, 0xffff0000, v12
	v_pk_add_f32 v[2:3], v[2:3], v[20:21] op_sel_hi:[1,0]
	v_pk_mul_f32 v[6:7], v[6:7], v[10:11]
	v_lshlrev_b32_e32 v10, 16, v28
	v_and_b32_e32 v11, 0xffff0000, v28
	v_pk_mul_f32 v[2:3], v[2:3], v[30:31]
	v_lshlrev_b32_e32 v30, 16, v26
	v_and_b32_e32 v31, 0xffff0000, v26
	v_pk_mul_f32 v[6:7], v[6:7], v[10:11]
	v_pk_add_f32 v[8:9], v[8:9], v[20:21] op_sel_hi:[1,0]
	v_lshlrev_b32_e32 v10, 16, v13
	v_and_b32_e32 v11, 0xffff0000, v13
	v_pk_mul_f32 v[2:3], v[2:3], v[30:31]
	v_pk_mul_f32 v[8:9], v[8:9], v[10:11]
	v_lshlrev_b32_e32 v10, 16, v29
	v_and_b32_e32 v11, 0xffff0000, v29
	v_pk_mul_f32 v[8:9], v[8:9], v[10:11]
	v_cvt_pk_bf16_f32 v2, v2, v3
	v_cvt_pk_bf16_f32 v3, v4, v5
	v_cvt_pk_bf16_f32 v4, v6, v7
	v_lshlrev_b64 v[6:7], 12, v[14:15]
	v_or_b32_e32 v14, s25, v1
	v_cvt_pk_bf16_f32 v5, v8, v9
	v_lshl_add_u64 v[6:7], v[16:17], 0, v[6:7]
	v_mad_i64_i32 v[10:11], s[2:3], v14, s69, v[66:67]
	global_store_dwordx4 v[6:7], v[2:5], off nt
	v_lshl_add_u64 v[20:21], v[10:11], 0, v[18:19]
	ds_read_b128 v[2:5], v24 offset:4224
	ds_read_b128 v[6:9], v24 offset:4240
	v_mov_b32_e32 v10, v112
	v_mov_b32_e32 v11, v113
	v_mov_b32_e32 v12, v114
	v_mov_b32_e32 v13, v115
	v_add_co_u32_e32 v20, vcc, s8, v20
	v_ashrrev_i32_e32 v15, 31, v14
	s_nop 0
	v_addc_co_u32_e32 v21, vcc, 0, v21, vcc
	v_mov_b32_e32 v26, v116
	v_mov_b32_e32 v27, v117
	v_mov_b32_e32 v28, v118
	v_mov_b32_e32 v29, v119
	s_nop 0
	v_mov_b32_e32 v20, v169
	v_or_b32_e32 v1, s17, v23
	v_lshlrev_b32_e32 v30, 16, v10
	v_and_b32_e32 v31, 0xffff0000, v10
	v_lshlrev_b32_e32 v10, 16, v11
	v_and_b32_e32 v11, 0xffff0000, v11
	s_waitcnt lgkmcnt(1)
	v_pk_add_f32 v[4:5], v[4:5], v[20:21] op_sel_hi:[1,0]
	s_nop 0
	v_pk_mul_f32 v[4:5], v[4:5], v[10:11]
	v_lshlrev_b32_e32 v10, 16, v27
	v_and_b32_e32 v11, 0xffff0000, v27
	v_pk_mul_f32 v[4:5], v[4:5], v[10:11]
	s_waitcnt lgkmcnt(0)
	v_pk_add_f32 v[6:7], v[6:7], v[20:21] op_sel_hi:[1,0]
	v_lshlrev_b32_e32 v10, 16, v12
	v_and_b32_e32 v11, 0xffff0000, v12
	v_pk_add_f32 v[2:3], v[2:3], v[20:21] op_sel_hi:[1,0]
	v_pk_mul_f32 v[6:7], v[6:7], v[10:11]
	v_lshlrev_b32_e32 v10, 16, v28
	v_and_b32_e32 v11, 0xffff0000, v28
	v_pk_mul_f32 v[2:3], v[2:3], v[30:31]
	v_lshlrev_b32_e32 v30, 16, v26
	v_and_b32_e32 v31, 0xffff0000, v26
	v_pk_mul_f32 v[6:7], v[6:7], v[10:11]
	v_pk_add_f32 v[8:9], v[8:9], v[20:21] op_sel_hi:[1,0]
	v_lshlrev_b32_e32 v10, 16, v13
	v_and_b32_e32 v11, 0xffff0000, v13
	v_pk_mul_f32 v[2:3], v[2:3], v[30:31]
	v_pk_mul_f32 v[8:9], v[8:9], v[10:11]
	v_lshlrev_b32_e32 v10, 16, v29
	v_and_b32_e32 v11, 0xffff0000, v29
	v_pk_mul_f32 v[8:9], v[8:9], v[10:11]
	v_cvt_pk_bf16_f32 v2, v2, v3
	v_cvt_pk_bf16_f32 v3, v4, v5
	v_cvt_pk_bf16_f32 v4, v6, v7
	v_lshlrev_b64 v[6:7], 12, v[14:15]
	v_or_b32_e32 v14, s25, v1
	v_cvt_pk_bf16_f32 v5, v8, v9
	v_lshl_add_u64 v[6:7], v[16:17], 0, v[6:7]
	v_mad_i64_i32 v[10:11], s[2:3], v14, s69, v[66:67]
	global_store_dwordx4 v[6:7], v[2:5], off nt
	v_lshl_add_u64 v[20:21], v[10:11], 0, v[18:19]
	ds_read_b128 v[2:5], v24 offset:6336
	ds_read_b128 v[6:9], v24 offset:6352
	v_mov_b32_e32 v10, v120
	v_mov_b32_e32 v11, v121
	v_mov_b32_e32 v12, v122
	v_mov_b32_e32 v13, v123
	v_add_co_u32_e32 v20, vcc, s8, v20
	v_ashrrev_i32_e32 v15, 31, v14
	s_nop 0
	v_addc_co_u32_e32 v21, vcc, 0, v21, vcc
	v_mov_b32_e32 v26, v124
	v_mov_b32_e32 v27, v125
	v_mov_b32_e32 v28, v126
	v_mov_b32_e32 v29, v127
	s_nop 0
	v_mov_b32_e32 v20, v170
	v_or_b32_e32 v1, s18, v23
	v_lshlrev_b32_e32 v30, 16, v10
	v_and_b32_e32 v31, 0xffff0000, v10
	v_lshlrev_b32_e32 v10, 16, v11
	v_and_b32_e32 v11, 0xffff0000, v11
	s_waitcnt lgkmcnt(1)
	v_pk_add_f32 v[4:5], v[4:5], v[20:21] op_sel_hi:[1,0]
	s_nop 0
	v_pk_mul_f32 v[4:5], v[4:5], v[10:11]
	v_lshlrev_b32_e32 v10, 16, v27
	v_and_b32_e32 v11, 0xffff0000, v27
	v_pk_mul_f32 v[4:5], v[4:5], v[10:11]
	s_waitcnt lgkmcnt(0)
	v_pk_add_f32 v[6:7], v[6:7], v[20:21] op_sel_hi:[1,0]
	v_lshlrev_b32_e32 v10, 16, v12
	v_and_b32_e32 v11, 0xffff0000, v12
	v_pk_add_f32 v[2:3], v[2:3], v[20:21] op_sel_hi:[1,0]
	v_pk_mul_f32 v[6:7], v[6:7], v[10:11]
	v_lshlrev_b32_e32 v10, 16, v28
	v_and_b32_e32 v11, 0xffff0000, v28
	v_pk_mul_f32 v[2:3], v[2:3], v[30:31]
	v_lshlrev_b32_e32 v30, 16, v26
	v_and_b32_e32 v31, 0xffff0000, v26
	v_pk_mul_f32 v[6:7], v[6:7], v[10:11]
	v_pk_add_f32 v[8:9], v[8:9], v[20:21] op_sel_hi:[1,0]
	v_lshlrev_b32_e32 v10, 16, v13
	v_and_b32_e32 v11, 0xffff0000, v13
	v_pk_mul_f32 v[2:3], v[2:3], v[30:31]
	v_pk_mul_f32 v[8:9], v[8:9], v[10:11]
	v_lshlrev_b32_e32 v10, 16, v29
	v_and_b32_e32 v11, 0xffff0000, v29
	v_pk_mul_f32 v[8:9], v[8:9], v[10:11]
	v_cvt_pk_bf16_f32 v2, v2, v3
	v_cvt_pk_bf16_f32 v3, v4, v5
	v_cvt_pk_bf16_f32 v4, v6, v7
	v_lshlrev_b64 v[6:7], 12, v[14:15]
	v_or_b32_e32 v14, s25, v1
	v_cvt_pk_bf16_f32 v5, v8, v9
	v_lshl_add_u64 v[6:7], v[16:17], 0, v[6:7]
	v_mad_i64_i32 v[10:11], s[2:3], v14, s69, v[66:67]
	global_store_dwordx4 v[6:7], v[2:5], off nt
	v_lshl_add_u64 v[20:21], v[10:11], 0, v[18:19]
	ds_read_b128 v[2:5], v24 offset:8448
	ds_read_b128 v[6:9], v24 offset:8464
	v_mov_b32_e32 v10, v128
	v_mov_b32_e32 v11, v129
	v_mov_b32_e32 v12, v130
	v_mov_b32_e32 v13, v131
	v_add_co_u32_e32 v20, vcc, s8, v20
	v_ashrrev_i32_e32 v15, 31, v14
	s_nop 0
	v_addc_co_u32_e32 v21, vcc, 0, v21, vcc
	v_mov_b32_e32 v26, v132
	v_mov_b32_e32 v27, v133
	v_mov_b32_e32 v28, v134
	v_mov_b32_e32 v29, v135
	s_nop 0
	v_mov_b32_e32 v20, v171
	v_or_b32_e32 v1, s19, v23
	v_lshlrev_b32_e32 v30, 16, v10
	v_and_b32_e32 v31, 0xffff0000, v10
	v_lshlrev_b32_e32 v10, 16, v11
	v_and_b32_e32 v11, 0xffff0000, v11
	s_waitcnt lgkmcnt(1)
	v_pk_add_f32 v[4:5], v[4:5], v[20:21] op_sel_hi:[1,0]
	s_nop 0
	v_pk_mul_f32 v[4:5], v[4:5], v[10:11]
	v_lshlrev_b32_e32 v10, 16, v27
	v_and_b32_e32 v11, 0xffff0000, v27
	v_pk_mul_f32 v[4:5], v[4:5], v[10:11]
	s_waitcnt lgkmcnt(0)
	v_pk_add_f32 v[6:7], v[6:7], v[20:21] op_sel_hi:[1,0]
	v_lshlrev_b32_e32 v10, 16, v12
	v_and_b32_e32 v11, 0xffff0000, v12
	v_pk_add_f32 v[2:3], v[2:3], v[20:21] op_sel_hi:[1,0]
	v_pk_mul_f32 v[6:7], v[6:7], v[10:11]
	v_lshlrev_b32_e32 v10, 16, v28
	v_and_b32_e32 v11, 0xffff0000, v28
	v_pk_mul_f32 v[2:3], v[2:3], v[30:31]
	v_lshlrev_b32_e32 v30, 16, v26
	v_and_b32_e32 v31, 0xffff0000, v26
	v_pk_mul_f32 v[6:7], v[6:7], v[10:11]
	v_pk_add_f32 v[8:9], v[8:9], v[20:21] op_sel_hi:[1,0]
	v_lshlrev_b32_e32 v10, 16, v13
	v_and_b32_e32 v11, 0xffff0000, v13
	v_pk_mul_f32 v[2:3], v[2:3], v[30:31]
	v_pk_mul_f32 v[8:9], v[8:9], v[10:11]
	v_lshlrev_b32_e32 v10, 16, v29
	v_and_b32_e32 v11, 0xffff0000, v29
	v_pk_mul_f32 v[8:9], v[8:9], v[10:11]
	v_cvt_pk_bf16_f32 v2, v2, v3
	v_cvt_pk_bf16_f32 v3, v4, v5
	v_cvt_pk_bf16_f32 v4, v6, v7
	v_lshlrev_b64 v[6:7], 12, v[14:15]
	v_or_b32_e32 v14, s25, v1
	v_cvt_pk_bf16_f32 v5, v8, v9
	v_lshl_add_u64 v[6:7], v[16:17], 0, v[6:7]
	v_mad_i64_i32 v[10:11], s[2:3], v14, s69, v[66:67]
	global_store_dwordx4 v[6:7], v[2:5], off nt
	v_lshl_add_u64 v[20:21], v[10:11], 0, v[18:19]
	ds_read_b128 v[2:5], v24 offset:10560
	ds_read_b128 v[6:9], v24 offset:10576
	v_mov_b32_e32 v10, v136
	v_mov_b32_e32 v11, v137
	v_mov_b32_e32 v12, v138
	v_mov_b32_e32 v13, v139
	v_add_co_u32_e32 v20, vcc, s8, v20
	v_ashrrev_i32_e32 v15, 31, v14
	s_nop 0
	v_addc_co_u32_e32 v21, vcc, 0, v21, vcc
	v_mov_b32_e32 v26, v140
	v_mov_b32_e32 v27, v141
	v_mov_b32_e32 v28, v142
	v_mov_b32_e32 v29, v143
	s_nop 0
	v_mov_b32_e32 v20, v172
	v_or_b32_e32 v1, s20, v23
	v_lshlrev_b32_e32 v30, 16, v10
	v_and_b32_e32 v31, 0xffff0000, v10
	v_lshlrev_b32_e32 v10, 16, v11
	v_and_b32_e32 v11, 0xffff0000, v11
	s_waitcnt lgkmcnt(1)
	v_pk_add_f32 v[4:5], v[4:5], v[20:21] op_sel_hi:[1,0]
	s_nop 0
	v_pk_mul_f32 v[4:5], v[4:5], v[10:11]
	v_lshlrev_b32_e32 v10, 16, v27
	v_and_b32_e32 v11, 0xffff0000, v27
	v_pk_mul_f32 v[4:5], v[4:5], v[10:11]
	s_waitcnt lgkmcnt(0)
	v_pk_add_f32 v[6:7], v[6:7], v[20:21] op_sel_hi:[1,0]
	v_lshlrev_b32_e32 v10, 16, v12
	v_and_b32_e32 v11, 0xffff0000, v12
	v_pk_add_f32 v[2:3], v[2:3], v[20:21] op_sel_hi:[1,0]
	v_pk_mul_f32 v[6:7], v[6:7], v[10:11]
	v_lshlrev_b32_e32 v10, 16, v28
	v_and_b32_e32 v11, 0xffff0000, v28
	v_pk_mul_f32 v[2:3], v[2:3], v[30:31]
	v_lshlrev_b32_e32 v30, 16, v26
	v_and_b32_e32 v31, 0xffff0000, v26
	v_pk_mul_f32 v[6:7], v[6:7], v[10:11]
	v_pk_add_f32 v[8:9], v[8:9], v[20:21] op_sel_hi:[1,0]
	v_lshlrev_b32_e32 v10, 16, v13
	v_and_b32_e32 v11, 0xffff0000, v13
	v_pk_mul_f32 v[2:3], v[2:3], v[30:31]
	v_pk_mul_f32 v[8:9], v[8:9], v[10:11]
	v_lshlrev_b32_e32 v10, 16, v29
	v_and_b32_e32 v11, 0xffff0000, v29
	v_pk_mul_f32 v[8:9], v[8:9], v[10:11]
	v_cvt_pk_bf16_f32 v2, v2, v3
	v_cvt_pk_bf16_f32 v3, v4, v5
	v_cvt_pk_bf16_f32 v4, v6, v7
	v_lshlrev_b64 v[6:7], 12, v[14:15]
	v_or_b32_e32 v14, s25, v1
	v_cvt_pk_bf16_f32 v5, v8, v9
	v_lshl_add_u64 v[6:7], v[16:17], 0, v[6:7]
	v_mad_i64_i32 v[10:11], s[2:3], v14, s69, v[66:67]
	global_store_dwordx4 v[6:7], v[2:5], off nt
	v_lshl_add_u64 v[20:21], v[10:11], 0, v[18:19]
	ds_read_b128 v[2:5], v24 offset:12672
	ds_read_b128 v[6:9], v24 offset:12688
	v_mov_b32_e32 v10, v152
	v_mov_b32_e32 v11, v153
	v_mov_b32_e32 v12, v154
	v_mov_b32_e32 v13, v155
	v_add_co_u32_e32 v20, vcc, s8, v20
	v_ashrrev_i32_e32 v15, 31, v14
	s_nop 0
	v_addc_co_u32_e32 v21, vcc, 0, v21, vcc
	v_mov_b32_e32 v26, v156
	v_mov_b32_e32 v27, v157
	v_mov_b32_e32 v28, v158
	v_mov_b32_e32 v29, v159
	s_nop 0
	v_mov_b32_e32 v20, v173
	v_or_b32_e32 v1, s21, v23
	v_lshlrev_b32_e32 v30, 16, v10
	v_and_b32_e32 v31, 0xffff0000, v10
	v_lshlrev_b32_e32 v10, 16, v11
	v_and_b32_e32 v11, 0xffff0000, v11
	s_waitcnt lgkmcnt(1)
	v_pk_add_f32 v[4:5], v[4:5], v[20:21] op_sel_hi:[1,0]
	s_nop 0
	v_pk_mul_f32 v[4:5], v[4:5], v[10:11]
	v_lshlrev_b32_e32 v10, 16, v27
	v_and_b32_e32 v11, 0xffff0000, v27
	v_pk_mul_f32 v[4:5], v[4:5], v[10:11]
	s_waitcnt lgkmcnt(0)
	v_pk_add_f32 v[6:7], v[6:7], v[20:21] op_sel_hi:[1,0]
	v_lshlrev_b32_e32 v10, 16, v12
	v_and_b32_e32 v11, 0xffff0000, v12
	v_pk_add_f32 v[2:3], v[2:3], v[20:21] op_sel_hi:[1,0]
	v_pk_mul_f32 v[6:7], v[6:7], v[10:11]
	v_lshlrev_b32_e32 v10, 16, v28
	v_and_b32_e32 v11, 0xffff0000, v28
	v_pk_mul_f32 v[2:3], v[2:3], v[30:31]
	v_lshlrev_b32_e32 v30, 16, v26
	v_and_b32_e32 v31, 0xffff0000, v26
	v_pk_mul_f32 v[6:7], v[6:7], v[10:11]
	v_pk_add_f32 v[8:9], v[8:9], v[20:21] op_sel_hi:[1,0]
	v_lshlrev_b32_e32 v10, 16, v13
	v_and_b32_e32 v11, 0xffff0000, v13
	v_pk_mul_f32 v[2:3], v[2:3], v[30:31]
	v_pk_mul_f32 v[8:9], v[8:9], v[10:11]
	v_lshlrev_b32_e32 v10, 16, v29
	v_and_b32_e32 v11, 0xffff0000, v29
	v_pk_mul_f32 v[8:9], v[8:9], v[10:11]
	v_cvt_pk_bf16_f32 v2, v2, v3
	v_cvt_pk_bf16_f32 v3, v4, v5
	v_cvt_pk_bf16_f32 v4, v6, v7
	v_lshlrev_b64 v[6:7], 12, v[14:15]
	v_or_b32_e32 v14, s25, v1
	v_cvt_pk_bf16_f32 v5, v8, v9
	v_lshl_add_u64 v[6:7], v[16:17], 0, v[6:7]
	v_mad_i64_i32 v[10:11], s[2:3], v14, s69, v[66:67]
	global_store_dwordx4 v[6:7], v[2:5], off nt
	v_lshl_add_u64 v[18:19], v[10:11], 0, v[18:19]
	ds_read_b128 v[2:5], v24 offset:14784
	ds_read_b128 v[6:9], v24 offset:14800
	v_mov_b32_e32 v10, v160
	v_mov_b32_e32 v11, v161
	v_mov_b32_e32 v12, v162
	v_mov_b32_e32 v13, v163
	v_add_co_u32_e32 v18, vcc, s8, v18
	v_ashrrev_i32_e32 v15, 31, v14
	s_nop 0
	v_addc_co_u32_e32 v19, vcc, 0, v19, vcc
	v_mov_b32_e32 v18, v164
	v_mov_b32_e32 v19, v165
	v_mov_b32_e32 v20, v166
	v_mov_b32_e32 v21, v167
	s_nop 0
	v_mov_b32_e32 v0, v174
	v_lshlrev_b32_e32 v22, 16, v10
	v_and_b32_e32 v23, 0xffff0000, v10
	v_lshlrev_b32_e32 v10, 16, v11
	v_and_b32_e32 v11, 0xffff0000, v11
	s_waitcnt lgkmcnt(1)
	v_pk_add_f32 v[4:5], v[4:5], v[0:1] op_sel_hi:[1,0]
	s_nop 0
	v_pk_mul_f32 v[4:5], v[4:5], v[10:11]
	v_lshlrev_b32_e32 v10, 16, v19
	v_and_b32_e32 v11, 0xffff0000, v19
	v_pk_add_f32 v[2:3], v[2:3], v[0:1] op_sel_hi:[1,0]
	v_pk_mul_f32 v[4:5], v[4:5], v[10:11]
	s_waitcnt lgkmcnt(0)
	v_pk_add_f32 v[6:7], v[6:7], v[0:1] op_sel_hi:[1,0]
	v_lshlrev_b32_e32 v10, 16, v12
	v_and_b32_e32 v11, 0xffff0000, v12
	v_pk_add_f32 v[0:1], v[8:9], v[0:1] op_sel_hi:[1,0]
	v_lshlrev_b32_e32 v8, 16, v13
	v_and_b32_e32 v9, 0xffff0000, v13
	v_pk_mul_f32 v[2:3], v[2:3], v[22:23]
	v_lshlrev_b32_e32 v22, 16, v18
	v_and_b32_e32 v23, 0xffff0000, v18
	v_pk_mul_f32 v[6:7], v[6:7], v[10:11]
	v_lshlrev_b32_e32 v10, 16, v20
	v_and_b32_e32 v11, 0xffff0000, v20
	v_pk_mul_f32 v[0:1], v[0:1], v[8:9]
	v_lshlrev_b32_e32 v8, 16, v21
	v_and_b32_e32 v9, 0xffff0000, v21
	v_pk_mul_f32 v[2:3], v[2:3], v[22:23]
	v_pk_mul_f32 v[6:7], v[6:7], v[10:11]
	v_pk_mul_f32 v[8:9], v[0:1], v[8:9]
	v_cvt_pk_bf16_f32 v1, v4, v5
	v_lshlrev_b64 v[4:5], 12, v[14:15]
	v_cvt_pk_bf16_f32 v0, v2, v3
	v_cvt_pk_bf16_f32 v2, v6, v7
	v_cvt_pk_bf16_f32 v3, v8, v9
	v_lshl_add_u64 v[4:5], v[16:17], 0, v[4:5]
	global_store_dwordx4 v[4:5], v[0:3], off nt
	s_cbranch_scc1 .LBB0_269

.LBB0_394:
	v_lshrrev_b32_e32 v15, 1, v190
	v_and_b32_e32 v15, 24, v15
	v_and_b32_e32 v14, 15, v190
	v_lshlrev_b32_e32 v16, 1, v15
	s_add_u32 s6, s70, 0x29100000
	v_lshl_or_b32 v140, s9, 6, v14
	v_lshl_or_b32 v14, v14, 6, v16
	v_lshlrev_b32_e32 v16, 2, v190
	s_sext_i32_i8 s11, s0
	s_addc_u32 s7, s71, 0
	s_lshl_b32 s0, s9, 13
	v_and_b32_e32 v16, 32, v16
	v_bitop3_b32 v17, v14, s0, v16 bitop3:0xde
	s_lshl_b32 s0, s12, 5
	s_and_b32 s14, s0, 0x60
	s_lshl_b32 s0, s14, 8
	s_add_i32 m0, s52, 0x18000
	v_lshl_add_u64 v[6:7], v[6:7], 0, s[30:31]
	v_bitop3_b32 v141, s0, v14, v16 bitop3:0xf6
	s_waitcnt vmcnt(2)
	s_barrier
	global_load_lds_dwordx4 v[6:7], off
	v_lshl_add_u64 v[4:5], v[4:5], 0, s[30:31]
	s_add_i32 m0, s52, 0x1a000
	s_add_i32 s0, s52, 0x8000
	s_add_i32 s56, s52, 0xa000
	global_load_lds_dwordx4 v[4:5], off
	v_lshl_add_u64 v[0:1], v[0:1], 0, s[30:31]
	s_mov_b32 m0, s0
	s_add_u32 s12, s22, 0x80080
	global_load_lds_dwordx4 v[0:1], off
	v_lshl_add_u64 v[0:1], v[2:3], 0, s[30:31]
	s_mov_b32 m0, s56
	s_addc_u32 s13, s23, 0
	global_load_lds_dwordx4 v[0:1], off
	s_add_i32 m0, s52, 0x1c000
	v_lshl_add_u64 v[0:1], s[12:13], 0, v[64:65]
	global_load_lds_dwordx4 v[0:1], off
	v_lshl_add_u64 v[0:1], s[12:13], 0, v[134:135]
	s_add_i32 m0, s52, 0x1e000
	s_cmpk_lt_u32 s8, 0x100
	global_load_lds_dwordx4 v[0:1], off
	v_lshlrev_b32_e32 v0, 15, v8
	v_and_b32_e32 v0, 0xffff0000, v0
	v_lshl_add_u32 v0, v9, 12, v0
	v_and_b32_e32 v1, 1, v8
	v_lshl_or_b32 v0, v1, 6, v0
	v_lshl_add_u32 v136, v10, 1, v0
	v_lshlrev_b32_e32 v0, 15, v11
	v_and_b32_e32 v0, 0xffff0000, v0
	s_waitcnt vmcnt(6)
	v_lshl_add_u32 v0, v12, 12, v0
	v_and_b32_e32 v1, 1, v11
	v_lshl_or_b32 v0, v1, 6, v0
	s_cselect_b64 s[8:9], -1, 0
	s_ashr_i32 s57, s42, 31
	v_lshl_or_b32 v142, s14, 1, v15
	v_mov_b32_e32 v137, v65
	v_lshl_add_u32 v138, v13, 1, v0
	v_mov_b32_e32 v139, v65
	s_mov_b32 s58, 0
	v_add_u32_e32 v143, 0, v17
	s_barrier
	s_branch .LBB0_397

.LBB0_404:
	s_add_u32 s22, s20, 0xfff80080
	s_addc_u32 s23, s21, -1
	s_add_i32 s65, 0, 0x10000
	s_cmp_eq_u32 s47, 28
	s_cselect_b32 s25, s15, s23
	s_cselect_b32 s24, s59, s22
	v_add_u32_e32 v152, s65, v141
	s_cselect_b32 s23, s13, s64
	s_cselect_b32 s22, s60, s61
	s_add_i32 s72, 0, 0x14000
	ds_read_b128 v[144:147], v152
	ds_read_b128 v[154:157], v152 offset:1024
	ds_read_b128 v[158:161], v152 offset:2048
	ds_read_b128 v[162:165], v152 offset:3072
	v_add_u32_e32 v152, s65, v141
	ds_read_b128 v[166:169], v152 offset:4096
	ds_read_b128 v[170:173], v152 offset:5120
	ds_read_b128 v[174:177], v152 offset:6144
	ds_read_b128 v[178:181], v152 offset:7168
	v_lshl_add_u64 v[152:153], s[20:21], 0, v[136:137]
	s_add_i32 m0, s52, 0xc000
	ds_read_b128 v[192:195], v143
	ds_read_b128 v[196:199], v143 offset:1024
	ds_read_b128 v[200:203], v143 offset:2048
	ds_read_b128 v[204:207], v143 offset:3072
	ds_read_b128 v[208:211], v143 offset:4096
	ds_read_b128 v[212:215], v143 offset:5120
	ds_read_b128 v[216:219], v143 offset:6144
	ds_read_b128 v[220:223], v143 offset:7168
	global_load_lds_dwordx4 v[152:153], off
	v_lshl_add_u64 v[152:153], s[20:21], 0, v[138:139]
	s_add_i32 m0, s52, 0xe000
	s_nop 0
	global_load_lds_dwordx4 v[152:153], off
	s_waitcnt vmcnt(8)
	s_waitcnt lgkmcnt(0)
	s_barrier
	s_setprio 1
	s_waitcnt lgkmcnt(0)
	v_mfma_f32_16x16x32_bf16 v[126:129], v[144:147], v[192:195], v[126:129]
	v_mfma_f32_16x16x32_bf16 v[122:125], v[158:161], v[192:195], v[122:125]
	v_mfma_f32_16x16x32_bf16 v[118:121], v[144:147], v[200:203], v[118:121]
	v_mfma_f32_16x16x32_bf16 v[114:117], v[158:161], v[200:203], v[114:117]
	v_mfma_f32_16x16x32_bf16 v[102:105], v[144:147], v[208:211], v[102:105]
	v_mfma_f32_16x16x32_bf16 v[98:101], v[158:161], v[208:211], v[98:101]
	v_mfma_f32_16x16x32_bf16 v[86:89], v[144:147], v[216:219], v[86:89]
	v_mfma_f32_16x16x32_bf16 v[82:85], v[158:161], v[216:219], v[82:85]
	v_mfma_f32_16x16x32_bf16 v[126:129], v[154:157], v[196:199], v[126:129]
	v_mfma_f32_16x16x32_bf16 v[122:125], v[162:165], v[196:199], v[122:125]
	v_mfma_f32_16x16x32_bf16 v[118:121], v[154:157], v[204:207], v[118:121]
	v_mfma_f32_16x16x32_bf16 v[114:117], v[162:165], v[204:207], v[114:117]
	v_mfma_f32_16x16x32_bf16 v[102:105], v[154:157], v[212:215], v[102:105]
	v_mfma_f32_16x16x32_bf16 v[98:101], v[162:165], v[212:215], v[98:101]
	v_mfma_f32_16x16x32_bf16 v[86:89], v[154:157], v[220:223], v[86:89]
	v_mfma_f32_16x16x32_bf16 v[82:85], v[162:165], v[220:223], v[82:85]
	s_setprio 0
	s_setprio 1
	v_mfma_f32_16x16x32_bf16 v[110:113], v[166:169], v[192:195], v[110:113]
	v_mfma_f32_16x16x32_bf16 v[106:109], v[174:177], v[192:195], v[106:109]
	v_mfma_f32_16x16x32_bf16 v[94:97], v[166:169], v[200:203], v[94:97]
	v_mfma_f32_16x16x32_bf16 v[90:93], v[174:177], v[200:203], v[90:93]
	v_mfma_f32_16x16x32_bf16 v[78:81], v[166:169], v[208:211], v[78:81]
	v_mfma_f32_16x16x32_bf16 v[74:77], v[174:177], v[208:211], v[74:77]
	v_mfma_f32_16x16x32_bf16 v[70:73], v[166:169], v[216:219], v[70:73]
	v_mfma_f32_16x16x32_bf16 v[66:69], v[174:177], v[216:219], v[66:69]
	v_mfma_f32_16x16x32_bf16 v[110:113], v[170:173], v[196:199], v[110:113]
	v_mfma_f32_16x16x32_bf16 v[106:109], v[178:181], v[196:199], v[106:109]
	v_mfma_f32_16x16x32_bf16 v[94:97], v[170:173], v[204:207], v[94:97]
	v_mfma_f32_16x16x32_bf16 v[90:93], v[178:181], v[204:207], v[90:93]
	v_mfma_f32_16x16x32_bf16 v[78:81], v[170:173], v[212:215], v[78:81]
	v_mfma_f32_16x16x32_bf16 v[74:77], v[178:181], v[212:215], v[74:77]
	v_mfma_f32_16x16x32_bf16 v[70:73], v[170:173], v[220:223], v[70:73]
	v_mfma_f32_16x16x32_bf16 v[66:69], v[178:181], v[220:223], v[66:69]
	s_setprio 0
	s_barrier
	s_add_i32 s65, s65, s29
	v_lshl_add_u64 v[152:153], s[22:23], 0, v[64:65]
	s_mov_b32 m0, s65
	ds_read_b128 v[192:195], v143 offset:16384
	ds_read_b128 v[196:199], v143 offset:17408
	ds_read_b128 v[200:203], v143 offset:18432
	ds_read_b128 v[204:207], v143 offset:19456
	ds_read_b128 v[208:211], v143 offset:20480
	ds_read_b128 v[212:215], v143 offset:21504
	ds_read_b128 v[216:219], v143 offset:22528
	ds_read_b128 v[220:223], v143 offset:23552
	global_load_lds_dwordx4 v[152:153], off
	s_add_i32 m0, s65, 0x2000
	s_add_u32 s66, s22, 0x80000
	v_lshl_add_u64 v[224:225], s[22:23], 0, v[134:135]
	s_addc_u32 s67, s23, 0
	s_add_i32 s65, s72, s29
	global_load_lds_dwordx4 v[224:225], off
	v_lshl_add_u64 v[226:227], s[66:67], 0, v[64:65]
	s_mov_b32 m0, s65
	v_lshl_add_u64 v[228:229], s[24:25], 0, v[132:133]
	global_load_lds_dwordx4 v[226:227], off
	v_lshl_add_u64 v[226:227], s[66:67], 0, v[134:135]
	s_add_i32 m0, s65, 0x2000
	s_nop 0
	global_load_lds_dwordx4 v[226:227], off
	v_lshl_add_u64 v[226:227], s[24:25], 0, v[130:131]
	s_mov_b32 m0, s52
	s_nop 0
	global_load_lds_dwordx4 v[226:227], off
	s_mov_b32 m0, s53
	s_nop 0
	global_load_lds_dwordx4 v[228:229], off
	s_waitcnt vmcnt(8)
	s_waitcnt lgkmcnt(0)
	s_barrier
	s_setprio 1
	s_waitcnt lgkmcnt(0)
	v_mfma_f32_16x16x32_bf16 v[60:63], v[144:147], v[192:195], v[60:63]
	v_mfma_f32_16x16x32_bf16 v[56:59], v[158:161], v[192:195], v[56:59]
	v_mfma_f32_16x16x32_bf16 v[52:55], v[144:147], v[200:203], v[52:55]
	v_mfma_f32_16x16x32_bf16 v[48:51], v[158:161], v[200:203], v[48:51]
	v_mfma_f32_16x16x32_bf16 v[36:39], v[144:147], v[208:211], v[36:39]
	v_mfma_f32_16x16x32_bf16 v[32:35], v[158:161], v[208:211], v[32:35]
	v_mfma_f32_16x16x32_bf16 v[20:23], v[144:147], v[216:219], v[20:23]
	v_mfma_f32_16x16x32_bf16 v[16:19], v[158:161], v[216:219], v[16:19]
	v_mfma_f32_16x16x32_bf16 v[60:63], v[154:157], v[196:199], v[60:63]
	v_mfma_f32_16x16x32_bf16 v[56:59], v[162:165], v[196:199], v[56:59]
	v_mfma_f32_16x16x32_bf16 v[52:55], v[154:157], v[204:207], v[52:55]
	v_mfma_f32_16x16x32_bf16 v[48:51], v[162:165], v[204:207], v[48:51]
	v_mfma_f32_16x16x32_bf16 v[36:39], v[154:157], v[212:215], v[36:39]
	v_mfma_f32_16x16x32_bf16 v[32:35], v[162:165], v[212:215], v[32:35]
	v_mfma_f32_16x16x32_bf16 v[20:23], v[154:157], v[220:223], v[20:23]
	v_mfma_f32_16x16x32_bf16 v[16:19], v[162:165], v[220:223], v[16:19]
	s_setprio 0
	s_setprio 1
	v_mfma_f32_16x16x32_bf16 v[44:47], v[166:169], v[192:195], v[44:47]
	v_mfma_f32_16x16x32_bf16 v[40:43], v[174:177], v[192:195], v[40:43]
	v_mfma_f32_16x16x32_bf16 v[28:31], v[166:169], v[200:203], v[28:31]
	v_mfma_f32_16x16x32_bf16 v[24:27], v[174:177], v[200:203], v[24:27]
	v_mfma_f32_16x16x32_bf16 v[12:15], v[166:169], v[208:211], v[12:15]
	v_mfma_f32_16x16x32_bf16 v[8:11], v[174:177], v[208:211], v[8:11]
	v_mfma_f32_16x16x32_bf16 v[4:7], v[166:169], v[216:219], v[4:7]
	v_mfma_f32_16x16x32_bf16 v[0:3], v[174:177], v[216:219], v[0:3]
	v_mfma_f32_16x16x32_bf16 v[44:47], v[170:173], v[196:199], v[44:47]
	v_mfma_f32_16x16x32_bf16 v[40:43], v[178:181], v[196:199], v[40:43]
	v_mfma_f32_16x16x32_bf16 v[28:31], v[170:173], v[204:207], v[28:31]
	v_mfma_f32_16x16x32_bf16 v[24:27], v[178:181], v[204:207], v[24:27]
	v_mfma_f32_16x16x32_bf16 v[12:15], v[170:173], v[212:215], v[12:15]
	v_mfma_f32_16x16x32_bf16 v[8:11], v[178:181], v[212:215], v[8:11]
	v_mfma_f32_16x16x32_bf16 v[4:7], v[170:173], v[220:223], v[4:7]
	v_mfma_f32_16x16x32_bf16 v[0:3], v[178:181], v[220:223], v[0:3]
	s_setprio 0
	s_barrier
	s_add_i32 s65, 0, 0x18000
	s_add_i32 s66, 0, 0x1c000
	v_add_u32_e32 v162, s65, v141
	v_add_u32_e32 v178, s65, v141
	ds_read_b128 v[144:147], v162
	ds_read_b128 v[154:157], v162 offset:1024
	ds_read_b128 v[158:161], v162 offset:2048
	ds_read_b128 v[162:165], v162 offset:3072
	ds_read_b128 v[166:169], v178 offset:4096
	ds_read_b128 v[170:173], v178 offset:5120
	ds_read_b128 v[174:177], v178 offset:6144
	ds_read_b128 v[178:181], v178 offset:7168
	s_add_u32 s24, s24, 0x80000
	s_addc_u32 s25, s25, 0
	s_mov_b32 m0, s54
	v_lshl_add_u64 v[230:231], s[24:25], 0, v[130:131]
	ds_read_b128 v[192:195], v143 offset:32768
	ds_read_b128 v[196:199], v143 offset:33792
	ds_read_b128 v[200:203], v143 offset:34816
	ds_read_b128 v[204:207], v143 offset:35840
	ds_read_b128 v[208:211], v143 offset:36864
	ds_read_b128 v[212:215], v143 offset:37888
	ds_read_b128 v[216:219], v143 offset:38912
	ds_read_b128 v[220:223], v143 offset:39936
	global_load_lds_dwordx4 v[230:231], off
	v_lshl_add_u64 v[230:231], s[24:25], 0, v[132:133]
	s_mov_b32 m0, s55
	s_nop 0
	global_load_lds_dwordx4 v[230:231], off
	s_waitcnt vmcnt(8)
	s_waitcnt lgkmcnt(0)
	s_barrier
	s_setprio 1
	s_waitcnt lgkmcnt(0)
	v_mfma_f32_16x16x32_bf16 v[126:129], v[144:147], v[192:195], v[126:129]
	v_mfma_f32_16x16x32_bf16 v[122:125], v[158:161], v[192:195], v[122:125]
	v_mfma_f32_16x16x32_bf16 v[118:121], v[144:147], v[200:203], v[118:121]
	v_mfma_f32_16x16x32_bf16 v[114:117], v[158:161], v[200:203], v[114:117]
	v_mfma_f32_16x16x32_bf16 v[102:105], v[144:147], v[208:211], v[102:105]
	v_mfma_f32_16x16x32_bf16 v[98:101], v[158:161], v[208:211], v[98:101]
	v_mfma_f32_16x16x32_bf16 v[86:89], v[144:147], v[216:219], v[86:89]
	v_mfma_f32_16x16x32_bf16 v[82:85], v[158:161], v[216:219], v[82:85]
	v_mfma_f32_16x16x32_bf16 v[126:129], v[154:157], v[196:199], v[126:129]
	v_mfma_f32_16x16x32_bf16 v[122:125], v[162:165], v[196:199], v[122:125]
	v_mfma_f32_16x16x32_bf16 v[118:121], v[154:157], v[204:207], v[118:121]
	v_mfma_f32_16x16x32_bf16 v[114:117], v[162:165], v[204:207], v[114:117]
	v_mfma_f32_16x16x32_bf16 v[102:105], v[154:157], v[212:215], v[102:105]
	v_mfma_f32_16x16x32_bf16 v[98:101], v[162:165], v[212:215], v[98:101]
	v_mfma_f32_16x16x32_bf16 v[86:89], v[154:157], v[220:223], v[86:89]
	v_mfma_f32_16x16x32_bf16 v[82:85], v[162:165], v[220:223], v[82:85]
	s_setprio 0
	s_setprio 1
	v_mfma_f32_16x16x32_bf16 v[110:113], v[166:169], v[192:195], v[110:113]
	v_mfma_f32_16x16x32_bf16 v[106:109], v[174:177], v[192:195], v[106:109]
	v_mfma_f32_16x16x32_bf16 v[94:97], v[166:169], v[200:203], v[94:97]
	v_mfma_f32_16x16x32_bf16 v[90:93], v[174:177], v[200:203], v[90:93]
	v_mfma_f32_16x16x32_bf16 v[78:81], v[166:169], v[208:211], v[78:81]
	v_mfma_f32_16x16x32_bf16 v[74:77], v[174:177], v[208:211], v[74:77]
	v_mfma_f32_16x16x32_bf16 v[70:73], v[166:169], v[216:219], v[70:73]
	v_mfma_f32_16x16x32_bf16 v[66:69], v[174:177], v[216:219], v[66:69]
	v_mfma_f32_16x16x32_bf16 v[110:113], v[170:173], v[196:199], v[110:113]
	v_mfma_f32_16x16x32_bf16 v[106:109], v[178:181], v[196:199], v[106:109]
	v_mfma_f32_16x16x32_bf16 v[94:97], v[170:173], v[204:207], v[94:97]
	v_mfma_f32_16x16x32_bf16 v[90:93], v[178:181], v[204:207], v[90:93]
	v_mfma_f32_16x16x32_bf16 v[78:81], v[170:173], v[212:215], v[78:81]
	v_mfma_f32_16x16x32_bf16 v[74:77], v[178:181], v[212:215], v[74:77]
	v_mfma_f32_16x16x32_bf16 v[70:73], v[170:173], v[220:223], v[70:73]
	v_mfma_f32_16x16x32_bf16 v[66:69], v[178:181], v[220:223], v[66:69]
	s_setprio 0
	s_barrier
	s_add_i32 s24, s65, s29
	v_lshl_add_u64 v[152:153], v[152:153], 0, s[30:31]
	s_mov_b32 m0, s24
	ds_read_b128 v[192:195], v143 offset:49152
	ds_read_b128 v[196:199], v143 offset:50176
	ds_read_b128 v[200:203], v143 offset:51200
	ds_read_b128 v[204:207], v143 offset:52224
	ds_read_b128 v[208:211], v143 offset:53248
	ds_read_b128 v[212:215], v143 offset:54272
	ds_read_b128 v[216:219], v143 offset:55296
	ds_read_b128 v[220:223], v143 offset:56320
	global_load_lds_dwordx4 v[152:153], off
	s_add_i32 m0, s24, 0x2000
	s_add_u32 s22, s22, 0x80080
	v_lshl_add_u64 v[152:153], v[224:225], 0, s[30:31]
	s_addc_u32 s23, s23, 0
	s_add_i32 s24, s66, s29
	global_load_lds_dwordx4 v[152:153], off
	v_lshl_add_u64 v[152:153], s[22:23], 0, v[64:65]
	s_mov_b32 m0, s24
	s_nop 0
	global_load_lds_dwordx4 v[152:153], off
	v_lshl_add_u64 v[152:153], s[22:23], 0, v[134:135]
	s_add_i32 m0, s24, 0x2000
	s_nop 0
	global_load_lds_dwordx4 v[152:153], off
	v_lshl_add_u64 v[152:153], v[226:227], 0, s[30:31]
	s_mov_b32 m0, s0
	s_nop 0
	global_load_lds_dwordx4 v[152:153], off
	v_lshl_add_u64 v[152:153], v[228:229], 0, s[30:31]
	s_mov_b32 m0, s56
	s_nop 0
	global_load_lds_dwordx4 v[152:153], off
	s_waitcnt vmcnt(8)
	s_waitcnt lgkmcnt(0)
	s_barrier
	s_setprio 1
	s_waitcnt lgkmcnt(0)
	v_mfma_f32_16x16x32_bf16 v[60:63], v[144:147], v[192:195], v[60:63]
	v_mfma_f32_16x16x32_bf16 v[56:59], v[158:161], v[192:195], v[56:59]
	v_mfma_f32_16x16x32_bf16 v[52:55], v[144:147], v[200:203], v[52:55]
	v_mfma_f32_16x16x32_bf16 v[48:51], v[158:161], v[200:203], v[48:51]
	v_mfma_f32_16x16x32_bf16 v[36:39], v[144:147], v[208:211], v[36:39]
	v_mfma_f32_16x16x32_bf16 v[32:35], v[158:161], v[208:211], v[32:35]
	v_mfma_f32_16x16x32_bf16 v[20:23], v[144:147], v[216:219], v[20:23]
	v_mfma_f32_16x16x32_bf16 v[16:19], v[158:161], v[216:219], v[16:19]
	v_mfma_f32_16x16x32_bf16 v[60:63], v[154:157], v[196:199], v[60:63]
	v_mfma_f32_16x16x32_bf16 v[56:59], v[162:165], v[196:199], v[56:59]
	v_mfma_f32_16x16x32_bf16 v[52:55], v[154:157], v[204:207], v[52:55]
	v_mfma_f32_16x16x32_bf16 v[48:51], v[162:165], v[204:207], v[48:51]
	v_mfma_f32_16x16x32_bf16 v[36:39], v[154:157], v[212:215], v[36:39]
	v_mfma_f32_16x16x32_bf16 v[32:35], v[162:165], v[212:215], v[32:35]
	v_mfma_f32_16x16x32_bf16 v[20:23], v[154:157], v[220:223], v[20:23]
	v_mfma_f32_16x16x32_bf16 v[16:19], v[162:165], v[220:223], v[16:19]
	s_setprio 0
	s_setprio 1
	v_mfma_f32_16x16x32_bf16 v[44:47], v[166:169], v[192:195], v[44:47]
	v_mfma_f32_16x16x32_bf16 v[40:43], v[174:177], v[192:195], v[40:43]
	v_mfma_f32_16x16x32_bf16 v[28:31], v[166:169], v[200:203], v[28:31]
	v_mfma_f32_16x16x32_bf16 v[24:27], v[174:177], v[200:203], v[24:27]
	v_mfma_f32_16x16x32_bf16 v[12:15], v[166:169], v[208:211], v[12:15]
	v_mfma_f32_16x16x32_bf16 v[8:11], v[174:177], v[208:211], v[8:11]
	v_mfma_f32_16x16x32_bf16 v[4:7], v[166:169], v[216:219], v[4:7]
	v_mfma_f32_16x16x32_bf16 v[0:3], v[174:177], v[216:219], v[0:3]
	v_mfma_f32_16x16x32_bf16 v[44:47], v[170:173], v[196:199], v[44:47]
	v_mfma_f32_16x16x32_bf16 v[40:43], v[178:181], v[196:199], v[40:43]
	v_mfma_f32_16x16x32_bf16 v[28:31], v[170:173], v[204:207], v[28:31]
	v_mfma_f32_16x16x32_bf16 v[24:27], v[178:181], v[204:207], v[24:27]
	v_mfma_f32_16x16x32_bf16 v[12:15], v[170:173], v[212:215], v[12:15]
	v_mfma_f32_16x16x32_bf16 v[8:11], v[178:181], v[212:215], v[8:11]
	v_mfma_f32_16x16x32_bf16 v[4:7], v[170:173], v[220:223], v[4:7]
	v_mfma_f32_16x16x32_bf16 v[0:3], v[178:181], v[220:223], v[0:3]
	s_setprio 0
	s_barrier
	s_add_i32 s47, s47, 2
	s_add_u32 s20, s20, 0x100
	s_addc_u32 s21, s21, 0
	s_add_u32 s61, s61, 0x100
	s_addc_u32 s64, s64, 0
	s_cmp_gt_u32 s47, 29
	s_cbranch_scc0 .LBB0_404
	s_and_b64 vcc, exec, s[8:9]
	s_cbranch_vccz .LBB0_407
	s_barrier
.LBB0_407:
	v_lshl_add_u32 v144, s10, 8, v140
	v_lshl_or_b32 v146, s11, 8, v142
	v_ashrrev_i32_e32 v145, 31, v144
	v_ashrrev_i32_e32 v147, 31, v146
	v_lshlrev_b64 v[152:153], 12, v[144:145]
	v_lshl_add_u64 v[152:153], s[6:7], 0, v[152:153]
	v_lshlrev_b64 v[146:147], 1, v[146:147]
	v_lshl_add_u64 v[152:153], v[152:153], 0, v[146:147]
	s_mov_b64 s[10:11], 0x80000
	v_cvt_pk_bf16_f32 v70, v70, v71
	v_cvt_pk_bf16_f32 v71, v72, v73
	v_cvt_pk_bf16_f32 v72, v66, v67
	v_lshl_add_u64 v[66:67], v[152:153], 0, s[10:11]
	s_mov_b32 s10, 0x80000
	v_cvt_pk_bf16_f32 v60, v60, v61
	v_cvt_pk_bf16_f32 v61, v62, v63
	v_cvt_pk_bf16_f32 v62, v56, v57
	v_add_co_u32_e32 v56, vcc, s10, v152
	v_cvt_pk_bf16_f32 v44, v44, v45
	v_cvt_pk_bf16_f32 v45, v46, v47
	v_cvt_pk_bf16_f32 v46, v40, v41
	v_cvt_pk_bf16_f32 v47, v42, v43
	s_mov_b64 s[10:11], 0x90000
	v_addc_co_u32_e32 v57, vcc, 0, v153, vcc
	global_store_dwordx4 v[66:67], v[44:47], off offset:64 nt
	v_cvt_pk_bf16_f32 v110, v110, v111
	v_cvt_pk_bf16_f32 v111, v112, v113
	v_lshl_add_u64 v[44:45], v[152:153], 0, s[10:11]
	s_mov_b32 s10, 0x90000
	v_cvt_pk_bf16_f32 v112, v106, v107
	v_or_b32_e32 v106, 16, v144
	v_add_co_u32_e32 v46, vcc, s10, v152
	v_cvt_pk_bf16_f32 v28, v28, v29
	v_cvt_pk_bf16_f32 v29, v30, v31
	v_cvt_pk_bf16_f32 v30, v24, v25
	v_cvt_pk_bf16_f32 v31, v26, v27
	s_mov_b64 s[10:11], 0xa0000
	v_ashrrev_i32_e32 v107, 31, v106
	v_cvt_pk_bf16_f32 v94, v94, v95
	v_cvt_pk_bf16_f32 v95, v96, v97
	v_cvt_pk_bf16_f32 v96, v90, v91
	v_or_b32_e32 v90, 32, v144
	v_addc_co_u32_e32 v47, vcc, 0, v153, vcc
	global_store_dwordx4 v[44:45], v[28:31], off offset:64 nt
	v_lshlrev_b64 v[106:107], 12, v[106:107]
	v_ashrrev_i32_e32 v91, 31, v90
	v_lshl_add_u64 v[28:29], v[152:153], 0, s[10:11]
	s_mov_b32 s10, 0xa0000
	v_cvt_pk_bf16_f32 v78, v78, v79
	v_cvt_pk_bf16_f32 v79, v80, v81
	v_cvt_pk_bf16_f32 v80, v74, v75
	v_or_b32_e32 v74, 48, v144
	v_add_co_u32_e32 v30, vcc, s10, v152
	v_cvt_pk_bf16_f32 v12, v12, v13
	v_cvt_pk_bf16_f32 v13, v14, v15
	v_cvt_pk_bf16_f32 v14, v8, v9
	v_cvt_pk_bf16_f32 v15, v10, v11
	s_mov_b64 s[10:11], 0xb0000
	v_cvt_pk_bf16_f32 v113, v108, v109
	v_lshl_add_u64 v[106:107], s[6:7], 0, v[106:107]
	v_lshlrev_b64 v[90:91], 12, v[90:91]
	v_ashrrev_i32_e32 v75, 31, v74
	v_addc_co_u32_e32 v31, vcc, 0, v153, vcc
	global_store_dwordx4 v[28:29], v[12:15], off offset:64 nt
	global_store_dwordx4 v[152:153], v[110:113], off offset:64 nt
	v_cvt_pk_bf16_f32 v97, v92, v93
	v_lshl_add_u64 v[12:13], v[152:153], 0, s[10:11]
	s_mov_b32 s10, 0xb0000
	v_lshl_add_u64 v[110:111], v[106:107], 0, v[146:147]
	v_lshl_add_u64 v[90:91], s[6:7], 0, v[90:91]
	v_lshlrev_b64 v[74:75], 12, v[74:75]
	v_add_co_u32_e32 v14, vcc, s10, v152
	global_store_dwordx4 v[110:111], v[94:97], off offset:64 nt
	v_cvt_pk_bf16_f32 v81, v76, v77
	v_lshl_add_u64 v[74:75], s[6:7], 0, v[74:75]
	v_lshl_add_u64 v[94:95], v[90:91], 0, v[146:147]
	v_addc_co_u32_e32 v15, vcc, 0, v153, vcc
	v_cvt_pk_bf16_f32 v126, v126, v127
	v_cvt_pk_bf16_f32 v127, v128, v129
	v_cvt_pk_bf16_f32 v128, v122, v123
	v_cvt_pk_bf16_f32 v129, v124, v125
	v_cvt_pk_bf16_f32 v106, v118, v119
	v_cvt_pk_bf16_f32 v107, v120, v121
	v_cvt_pk_bf16_f32 v108, v114, v115
	v_cvt_pk_bf16_f32 v109, v116, v117
	v_cvt_pk_bf16_f32 v90, v102, v103
	v_cvt_pk_bf16_f32 v91, v104, v105
	v_cvt_pk_bf16_f32 v92, v98, v99
	v_cvt_pk_bf16_f32 v93, v100, v101
	global_store_dwordx4 v[94:95], v[78:81], off offset:64 nt
	v_cvt_pk_bf16_f32 v76, v82, v83
	v_cvt_pk_bf16_f32 v77, v84, v85
	v_lshl_add_u64 v[78:79], v[74:75], 0, v[146:147]
	v_cvt_pk_bf16_f32 v74, v86, v87
	v_cvt_pk_bf16_f32 v75, v88, v89
	v_cvt_pk_bf16_f32 v73, v68, v69
	v_cvt_pk_bf16_f32 v63, v58, v59
	v_cvt_pk_bf16_f32 v40, v52, v53
	v_cvt_pk_bf16_f32 v41, v54, v55
	v_cvt_pk_bf16_f32 v42, v48, v49
	v_cvt_pk_bf16_f32 v43, v50, v51
	v_cvt_pk_bf16_f32 v24, v36, v37
	v_cvt_pk_bf16_f32 v25, v38, v39
	v_cvt_pk_bf16_f32 v26, v32, v33
	v_cvt_pk_bf16_f32 v27, v34, v35
	v_cvt_pk_bf16_f32 v8, v20, v21
	v_cvt_pk_bf16_f32 v9, v22, v23
	v_cvt_pk_bf16_f32 v10, v16, v17
	v_cvt_pk_bf16_f32 v11, v18, v19
	v_cvt_pk_bf16_f32 v4, v4, v5
	v_cvt_pk_bf16_f32 v5, v6, v7
	v_cvt_pk_bf16_f32 v6, v0, v1
	v_cvt_pk_bf16_f32 v7, v2, v3
	s_andn2_b64 vcc, exec, s[62:63]
	s_mov_b64 s[10:11], -1
	global_store_dwordx4 v[152:153], v[126:129], off nt
	global_store_dwordx4 v[110:111], v[106:109], off nt
	global_store_dwordx4 v[94:95], v[90:93], off nt
	global_store_dwordx4 v[78:79], v[74:77], off nt
	global_store_dwordx4 v[78:79], v[70:73], off offset:64 nt
	global_store_dwordx4 v[56:57], v[60:63], off nt
	global_store_dwordx4 v[46:47], v[40:43], off nt
	global_store_dwordx4 v[30:31], v[24:27], off nt
	global_store_dwordx4 v[14:15], v[8:11], off nt
	global_store_dwordx4 v[12:13], v[4:7], off offset:64 nt
	s_cbranch_vccnz .LBB0_396
	s_andn2_b64 vcc, exec, s[4:5]
	s_cbranch_vccnz .LBB0_395
	s_barrier
	s_branch .LBB0_395

.LBB0_412:
	s_add_i32 s0, s50, 6
	s_cmp_gt_u32 s0, 12
	s_mov_b64 s[4:5], -1
	s_cbranch_scc0 .LBB0_417
	s_lshl_b32 s0, s34, 3
	v_readlane_b32 s2, v255, 18
	s_add_i32 s4, s2, s0
	s_cmpk_gt_i32 s4, 0x3fff
	s_cbranch_scc1 .LBB0_416
	v_readlane_b32 s2, v253, 43
	v_lshlrev_b32_e32 v64, 4, v189
	v_readlane_b32 s3, v253, 44
	s_waitcnt vmcnt(0)
	v_and_b32_e32 v0, 64, v185
	v_add_u32_e32 v0, 64, v0
	v_lshl_add_u64 v[38:39], s[2:3], 0, v[64:65]
	v_readlane_b32 s2, v253, 45
	v_readlane_b32 s3, v253, 46
	v_xor_b32_e32 v1, 32, v185
	v_cmp_lt_i32_e32 vcc, v1, v0
	v_lshl_add_u64 v[40:41], s[2:3], 0, v[64:65]
	v_readlane_b32 s2, v253, 47
	v_readlane_b32 s3, v253, 48
	v_cndmask_b32_e32 v1, v185, v1, vcc
	v_lshlrev_b32_e32 v75, 2, v1
	v_lshl_add_u64 v[42:43], s[2:3], 0, v[64:65]
	v_readlane_b32 s2, v253, 49
	v_readlane_b32 s3, v253, 50
	v_xor_b32_e32 v1, 16, v185
	v_cmp_lt_i32_e32 vcc, v1, v0
	v_lshl_add_u64 v[44:45], s[2:3], 0, v[64:65]
	v_readlane_b32 s2, v253, 41
	v_readlane_b32 s3, v253, 42
	v_cndmask_b32_e32 v1, v185, v1, vcc
	v_lshlrev_b32_e32 v94, 2, v1
	v_lshl_add_u64 v[46:47], s[2:3], 0, v[64:65]
	v_readlane_b32 s2, v253, 51
	v_readlane_b32 s3, v253, 52
	v_xor_b32_e32 v1, 8, v185
	v_cmp_lt_i32_e32 vcc, v1, v0
	v_lshl_add_u64 v[48:49], s[2:3], 0, v[64:65]
	v_readlane_b32 s2, v253, 53
	v_readlane_b32 s3, v253, 54
	v_cndmask_b32_e32 v1, v185, v1, vcc
	v_lshlrev_b32_e32 v95, 2, v1
	v_lshl_add_u64 v[50:51], s[2:3], 0, v[64:65]
	v_readlane_b32 s2, v253, 55
	v_readlane_b32 s3, v253, 56
	v_xor_b32_e32 v1, 4, v185
	v_cmp_lt_i32_e32 vcc, v1, v0
	v_lshl_add_u64 v[52:53], s[2:3], 0, v[64:65]
	v_readlane_b32 s2, v253, 57
	v_readlane_b32 s3, v253, 58
	v_cndmask_b32_e32 v1, v185, v1, vcc
	v_lshlrev_b32_e32 v96, 2, v1
	v_lshl_add_u64 v[54:55], s[2:3], 0, v[64:65]
	v_readlane_b32 s2, v253, 59
	v_readlane_b32 s3, v253, 60
	v_xor_b32_e32 v1, 2, v185
	v_cmp_lt_i32_e32 vcc, v1, v0
	v_lshl_add_u64 v[56:57], s[2:3], 0, v[64:65]
	v_readlane_b32 s2, v253, 61
	v_readlane_b32 s3, v253, 62
	v_cndmask_b32_e32 v1, v185, v1, vcc
	v_lshlrev_b32_e32 v97, 2, v1
	v_lshl_add_u64 v[58:59], s[2:3], 0, v[64:65]
	v_readlane_b32 s2, v253, 63
	v_xor_b32_e32 v1, 1, v185
	v_readlane_b32 s3, v254, 0
	s_ashr_i32 s5, s4, 31
	v_cmp_lt_i32_e32 vcc, v1, v0
	v_lshl_add_u64 v[60:61], s[2:3], 0, v[64:65]
	s_waitcnt lgkmcnt(0)
	s_lshl_b32 s6, s42, 3
	s_lshl_b64 s[2:3], s[4:5], 12
	v_cndmask_b32_e32 v0, v185, v1, vcc
	s_add_u32 s2, s70, s2
	v_lshlrev_b32_e32 v98, 2, v0
	v_lshlrev_b32_e32 v0, 3, v189
	v_mov_b32_e32 v1, v65
	s_addc_u32 s3, s71, s3
	v_lshl_add_u64 v[0:1], s[2:3], 0, v[0:1]
	s_mov_b64 s[2:3], 0x29100000
	s_ashr_i32 s7, s6, 31
	v_lshl_add_u64 v[62:63], v[0:1], 0, s[2:3]
	s_lshl_b64 s[8:9], s[6:7], 12
	s_lshl_b64 s[2:3], s[4:5], 13
	v_readlane_b32 s12, v252, 9
	v_readlane_b32 s52, v252, 1
	v_readlane_b32 s13, v252, 10
	s_add_u32 s10, s12, s2
	v_readlane_b32 s56, v252, 5
	v_readlane_b32 s14, v252, 11
	s_addc_u32 s11, s13, s3
	s_lshl_b64 s[12:13], s[6:7], 13
	v_readlane_b32 s54, v252, 3
	v_readlane_b32 s55, v252, 4
	v_readlane_b32 s57, v252, 6
	v_readlane_b32 s15, v252, 12
	s_add_u32 s14, s56, s2
	v_lshl_add_u64 v[36:37], s[54:55], 0, v[64:65]
	s_addc_u32 s15, s57, s3
	v_readlane_b32 s53, v252, 2
	v_readlane_b32 s58, v252, 7
	v_readlane_b32 s59, v252, 8
	v_readlane_b32 s16, v252, 13
	v_readlane_b32 s17, v252, 14
	v_readlane_b32 s18, v252, 15
	v_readlane_b32 s19, v252, 16
	v_readlane_b32 s20, v252, 17
	v_readlane_b32 s21, v252, 18
	v_readlane_b32 s22, v252, 19
	v_readlane_b32 s23, v252, 20
	v_readlane_b32 s24, v252, 21
	v_readlane_b32 s25, v252, 22
	v_readlane_b32 s26, v252, 23
	v_readlane_b32 s27, v252, 24
	global_load_dwordx4 v[114:117], v[36:37], off offset:1024
	global_load_dwordx4 v[118:121], v[36:37], off offset:2048
	global_load_dwordx4 v[122:125], v[36:37], off offset:3072
	global_load_dwordx4 v[126:129], v[38:39], off
	global_load_dwordx4 v[130:133], v[40:41], off
	global_load_dwordx4 v[134:137], v[42:43], off
	global_load_dwordx4 v[138:141], v[44:45], off
	global_load_dwordx4 v[142:145], v[46:47], off
	global_load_dwordx4 v[152:155], v[48:49], off
	global_load_dwordx4 v[156:159], v[50:51], off
	global_load_dwordx4 v[160:163], v[52:53], off
	global_load_dwordx4 v[164:167], v[54:55], off
	global_load_dwordx4 v[168:171], v[56:57], off
	global_load_dwordx4 v[172:175], v[58:59], off
	global_load_dwordx4 v[176:179], v[60:61], off
	s_waitcnt vmcnt(0)
.LBB0_415:
	global_load_dwordx2 v[4:5], v[62:63], off nt
	global_load_dwordx2 v[6:7], v[62:63], off offset:512 nt
	global_load_dwordx2 v[32:33], v[62:63], off offset:1024 nt
	global_load_dwordx2 v[34:35], v[62:63], off offset:1536 nt
	global_load_dwordx2 v[68:69], v[62:63], off offset:2560 nt
	global_load_dwordx2 v[66:67], v[62:63], off offset:2048 nt
	global_load_dwordx2 v[72:73], v[62:63], off offset:3584 nt
	global_load_dwordx2 v[108:109], v[62:63], off offset:3072 nt
	global_load_dwordx4 v[100:103], v[36:37], off
	v_lshl_add_u64 v[0:1], s[10:11], 0, v[64:65]
	global_load_dwordx4 v[104:107], v[0:1], off nt
	global_load_dwordx4 v[16:19], v[0:1], off offset:1024 nt
	global_load_dwordx4 v[8:11], v[0:1], off offset:2048 nt
	global_load_dwordx4 v[12:15], v[0:1], off offset:3072 nt
	v_add_co_u32_e32 v0, vcc, 0x1000, v0
	v_lshl_add_u64 v[80:81], s[14:15], 0, v[64:65]
	s_nop 0
	v_addc_co_u32_e32 v1, vcc, 0, v1, vcc
	global_load_dwordx4 v[20:23], v[0:1], off nt
	global_load_dwordx4 v[24:27], v[0:1], off offset:1024 nt
	global_load_dwordx4 v[28:31], v[0:1], off offset:2048 nt
	s_nop 0
	global_load_dwordx4 v[0:3], v[0:1], off offset:3072 nt
	s_movk_i32 s0, 0x1000
	s_add_i32 s4, s4, s6
	s_add_u32 s10, s10, s12
	s_addc_u32 s11, s11, s13
	s_add_u32 s14, s14, s12
	s_addc_u32 s15, s15, s13
	s_cmpk_lt_i32 s4, 0x4000
	s_waitcnt vmcnt(16)
	v_and_b32_e32 v111, 0xffff0000, v4
	s_waitcnt vmcnt(15)
	v_and_b32_e32 v93, 0xffff0000, v6
	v_lshlrev_b32_e32 v110, 16, v4
	v_lshlrev_b32_e32 v92, 16, v6
	s_waitcnt vmcnt(14)
	v_and_b32_e32 v89, 0xffff0000, v32
	v_mul_f32_e32 v74, v111, v111
	v_mul_f32_e32 v99, v93, v93
	v_lshlrev_b32_e32 v4, 16, v5
	v_lshlrev_b32_e32 v90, 16, v7
	v_lshlrev_b32_e32 v88, 16, v32
	s_waitcnt vmcnt(13)
	v_and_b32_e32 v85, 0xffff0000, v34
	v_mul_f32_e32 v112, v89, v89
	v_fmac_f32_e32 v74, v110, v110
	v_fmac_f32_e32 v99, v92, v92
	v_and_b32_e32 v5, 0xffff0000, v5
	v_and_b32_e32 v91, 0xffff0000, v7
	v_lshlrev_b32_e32 v86, 16, v33
	v_and_b32_e32 v87, 0xffff0000, v33
	v_lshlrev_b32_e32 v84, 16, v34
	s_waitcnt vmcnt(12)
	v_and_b32_e32 v33, 0xffff0000, v68
	s_waitcnt vmcnt(11)
	v_and_b32_e32 v32, 0xffff0000, v66
	v_mul_f32_e32 v113, v85, v85
	v_fmac_f32_e32 v112, v88, v88
	v_fmac_f32_e32 v74, v4, v4
	v_fmac_f32_e32 v99, v90, v90
	v_lshlrev_b32_e32 v82, 16, v35
	v_and_b32_e32 v83, 0xffff0000, v35
	v_lshlrev_b32_e32 v35, 16, v68
	v_lshlrev_b32_e32 v34, 16, v66
	v_pk_mul_f32 v[6:7], v[32:33], v[32:33]
	v_fmac_f32_e32 v113, v84, v84
	v_fmac_f32_e32 v112, v86, v86
	v_fmac_f32_e32 v74, v5, v5
	v_fmac_f32_e32 v99, v91, v91
	v_lshlrev_b32_e32 v77, 16, v69
	v_lshlrev_b32_e32 v76, 16, v67
	v_and_b32_e32 v78, 0xffff0000, v67
	s_waitcnt vmcnt(10)
	v_and_b32_e32 v67, 0xffff0000, v72
	s_waitcnt vmcnt(9)
	v_and_b32_e32 v66, 0xffff0000, v108
	v_pk_fma_f32 v[6:7], v[34:35], v[34:35], v[6:7]
	v_fmac_f32_e32 v113, v82, v82
	v_fmac_f32_e32 v112, v87, v87
	v_add_f32_e32 v74, v74, v99
	v_and_b32_e32 v79, 0xffff0000, v69
	v_lshlrev_b32_e32 v69, 16, v72
	v_lshlrev_b32_e32 v68, 16, v108
	v_lshlrev_b32_e32 v70, 16, v109
	v_and_b32_e32 v72, 0xffff0000, v109
	v_pk_mul_f32 v[108:109], v[66:67], v[66:67]
	v_pk_fma_f32 v[6:7], v[76:77], v[76:77], v[6:7]
	v_fmac_f32_e32 v113, v83, v83
	v_add_f32_e32 v74, v74, v112
	v_lshlrev_b32_e32 v71, 16, v73
	v_pk_fma_f32 v[108:109], v[68:69], v[68:69], v[108:109]
	v_pk_fma_f32 v[6:7], v[78:79], v[78:79], v[6:7]
	v_add_f32_e32 v74, v74, v113
	v_and_b32_e32 v73, 0xffff0000, v73
	v_pk_fma_f32 v[108:109], v[70:71], v[70:71], v[108:109]
	v_add_f32_e32 v6, v74, v6
	v_pk_fma_f32 v[108:109], v[72:73], v[72:73], v[108:109]
	v_add_f32_e32 v6, v6, v7
	v_add_f32_e32 v6, v6, v108
	v_add_f32_e32 v6, v6, v109
	ds_bpermute_b32 v7, v75, v6
	s_waitcnt lgkmcnt(0)
	v_add_f32_e32 v6, v6, v7
	ds_bpermute_b32 v7, v94, v6
	s_waitcnt lgkmcnt(0)
	v_add_f32_e32 v6, v6, v7
	ds_bpermute_b32 v7, v95, v6
	s_waitcnt lgkmcnt(0)
	v_add_f32_e32 v6, v6, v7
	ds_bpermute_b32 v7, v96, v6
	s_waitcnt lgkmcnt(0)
	v_add_f32_e32 v6, v6, v7
	ds_bpermute_b32 v7, v97, v6
	s_waitcnt lgkmcnt(0)
	v_add_f32_e32 v6, v6, v7
	ds_bpermute_b32 v7, v98, v6
	s_waitcnt lgkmcnt(0)
	v_add_f32_e32 v6, v6, v7
	v_fmamk_f32 v6, v6, 0x3a000000, v184
	v_mul_f32_e32 v7, 0x4b800000, v6
	v_cmp_gt_f32_e32 vcc, s92, v6
	s_nop 1
	v_cndmask_b32_e32 v6, v6, v7, vcc
	v_rsq_f32_e32 v6, v6
	s_nop 0
	v_mul_f32_e32 v7, 0x45800000, v6
	v_cndmask_b32_e32 v74, v6, v7, vcc
	v_pk_mul_f32 v[108:109], v[110:111], v[74:75] op_sel_hi:[1,0]
	v_pk_mul_f32 v[4:5], v[4:5], v[74:75] op_sel_hi:[1,0]
	v_pk_mul_f32 v[92:93], v[92:93], v[74:75] op_sel_hi:[1,0]
	s_waitcnt vmcnt(7)
	v_pk_fma_f32 v[6:7], v[102:103], v[4:5], v[106:107]
	v_pk_fma_f32 v[4:5], v[100:101], v[108:109], v[104:105]
	global_store_dwordx4 v[80:81], v[4:7], off nt
	v_mov_b32_e32 v102, v116
	v_mov_b32_e32 v103, v117
	v_mov_b32_e32 v100, v114
	v_mov_b32_e32 v101, v115
	v_pk_mul_f32 v[90:91], v[90:91], v[74:75] op_sel_hi:[1,0]
	v_pk_mul_f32 v[88:89], v[88:89], v[74:75] op_sel_hi:[1,0]
	v_pk_mul_f32 v[86:87], v[86:87], v[74:75] op_sel_hi:[1,0]
	v_pk_mul_f32 v[84:85], v[84:85], v[74:75] op_sel_hi:[1,0]
	v_pk_mul_f32 v[82:83], v[82:83], v[74:75] op_sel_hi:[1,0]
	s_waitcnt vmcnt(7)
	v_pk_fma_f32 v[18:19], v[102:103], v[90:91], v[18:19]
	v_pk_fma_f32 v[16:17], v[100:101], v[92:93], v[16:17]
	global_store_dwordx4 v[80:81], v[16:19], off offset:1024 nt
	v_mov_b32_e32 v92, v120
	v_mov_b32_e32 v93, v121
	v_mov_b32_e32 v90, v118
	v_mov_b32_e32 v91, v119
	s_waitcnt vmcnt(7)
	v_pk_fma_f32 v[10:11], v[92:93], v[86:87], v[10:11]
	v_pk_fma_f32 v[8:9], v[90:91], v[88:89], v[8:9]
	global_store_dwordx4 v[80:81], v[8:11], off offset:2048 nt
	v_mov_b32_e32 v88, v124
	v_mov_b32_e32 v89, v125
	v_mov_b32_e32 v86, v122
	v_mov_b32_e32 v87, v123
	s_waitcnt vmcnt(7)
	v_pk_fma_f32 v[14:15], v[88:89], v[82:83], v[14:15]
	v_pk_fma_f32 v[12:13], v[86:87], v[84:85], v[12:13]
	global_store_dwordx4 v[80:81], v[12:15], off offset:3072 nt
	v_mov_b32_e32 v84, v128
	v_mov_b32_e32 v85, v129
	v_mov_b32_e32 v82, v126
	v_mov_b32_e32 v83, v127
	v_mov_b32_e32 v86, v76
	v_mov_b32_e32 v87, v78
	v_mov_b32_e32 v88, v34
	v_mov_b32_e32 v89, v32
	v_add_co_u32_e32 v80, vcc, s0, v80
	v_pk_mul_f32 v[86:87], v[86:87], v[74:75] op_sel_hi:[1,0]
	v_pk_mul_f32 v[88:89], v[88:89], v[74:75] op_sel_hi:[1,0]
	v_addc_co_u32_e32 v81, vcc, 0, v81, vcc
	v_mov_b32_e32 v32, v35
	v_mov_b32_e32 v78, v77
	v_pk_mul_f32 v[34:35], v[78:79], v[74:75] op_sel_hi:[1,0]
	v_pk_mul_f32 v[32:33], v[32:33], v[74:75] op_sel_hi:[1,0]
	v_mov_b32_e32 v76, v70
	v_mov_b32_e32 v77, v72
	v_mov_b32_e32 v78, v68
	v_mov_b32_e32 v79, v66
	v_pk_mul_f32 v[76:77], v[76:77], v[74:75] op_sel_hi:[1,0]
	v_pk_mul_f32 v[78:79], v[78:79], v[74:75] op_sel_hi:[1,0]
	v_mov_b32_e32 v66, v69
	v_mov_b32_e32 v72, v71
	v_pk_mul_f32 v[68:69], v[72:73], v[74:75] op_sel_hi:[1,0]
	v_pk_mul_f32 v[66:67], v[66:67], v[74:75] op_sel_hi:[1,0]
	v_mul_f32_e32 v70, v5, v5
	v_mul_f32_e32 v71, v17, v17
	v_fmac_f32_e32 v70, v4, v4
	v_fmac_f32_e32 v71, v16, v16
	v_fmac_f32_e32 v70, v6, v6
	v_fmac_f32_e32 v71, v18, v18
	v_fmac_f32_e32 v70, v7, v7
	v_fmac_f32_e32 v71, v19, v19
	v_add_f32_e32 v70, v70, v71
	v_mul_f32_e32 v71, v9, v9
	v_fmac_f32_e32 v71, v8, v8
	v_fmac_f32_e32 v71, v10, v10
	v_fmac_f32_e32 v71, v11, v11
	v_add_f32_e32 v70, v71, v70
	v_mul_f32_e32 v71, v13, v13
	v_fmac_f32_e32 v71, v12, v12
	v_fmac_f32_e32 v71, v14, v14
	v_fmac_f32_e32 v71, v15, v15
	v_add_f32_e32 v74, v71, v70
	s_brev_b32 s0, 59
	s_waitcnt vmcnt(7)
	v_pk_fma_f32 v[20:21], v[82:83], v[88:89], v[20:21]
	v_pk_fma_f32 v[22:23], v[84:85], v[86:87], v[22:23]
	global_store_dwordx4 v[80:81], v[20:23], off nt
	v_mov_b32_e32 v84, v132
	v_mov_b32_e32 v85, v133
	v_mov_b32_e32 v82, v130
	v_mov_b32_e32 v83, v131
	v_mov_b32_e32 v73, v21
	v_mov_b32_e32 v71, v20
	s_waitcnt vmcnt(7)
	v_pk_fma_f32 v[24:25], v[82:83], v[32:33], v[24:25]
	v_pk_fma_f32 v[26:27], v[84:85], v[34:35], v[26:27]
	global_store_dwordx4 v[80:81], v[24:27], off offset:1024 nt
	v_mov_b32_e32 v34, v136
	v_mov_b32_e32 v35, v137
	v_mov_b32_e32 v32, v134
	v_mov_b32_e32 v33, v135
	v_mov_b32_e32 v72, v25
	v_mov_b32_e32 v70, v24
	v_pk_mul_f32 v[72:73], v[72:73], v[72:73]
	v_mov_b32_e32 v83, v23
	v_pk_fma_f32 v[70:71], v[70:71], v[70:71], v[72:73]
	v_mov_b32_e32 v82, v27
	s_waitcnt vmcnt(7)
	v_pk_fma_f32 v[28:29], v[32:33], v[78:79], v[28:29]
	v_pk_fma_f32 v[30:31], v[34:35], v[76:77], v[30:31]
	global_store_dwordx4 v[80:81], v[28:31], off offset:2048 nt
	v_mov_b32_e32 v34, v140
	v_mov_b32_e32 v35, v141
	v_mov_b32_e32 v32, v138
	v_mov_b32_e32 v33, v139
	v_mov_b32_e32 v79, v22
	v_mov_b32_e32 v78, v26
	v_pk_fma_f32 v[70:71], v[78:79], v[78:79], v[70:71]
	v_mov_b32_e32 v73, v31
	v_pk_fma_f32 v[70:71], v[82:83], v[82:83], v[70:71]
	v_add_co_u32_e32 v76, vcc, s0, v62
	v_add_f32_e32 v71, v71, v74
	v_add_f32_e32 v74, v70, v71
	v_mov_b32_e32 v71, v30
	v_addc_co_u32_e32 v77, vcc, -1, v63, vcc
	s_mov_b32 s0, 0xdc001000
	s_waitcnt vmcnt(7)
	v_pk_fma_f32 v[0:1], v[32:33], v[66:67], v[0:1]
	v_pk_fma_f32 v[2:3], v[34:35], v[68:69], v[2:3]
	global_store_dwordx4 v[80:81], v[0:3], off offset:3072 nt
	v_mov_b32_e32 v68, v144
	v_mov_b32_e32 v69, v145
	v_mov_b32_e32 v66, v142
	v_mov_b32_e32 v67, v143
	v_mov_b32_e32 v35, v29
	v_mov_b32_e32 v34, v1
	v_mov_b32_e32 v33, v28
	v_mov_b32_e32 v32, v0
	v_pk_mul_f32 v[34:35], v[34:35], v[34:35]
	v_mov_b32_e32 v70, v2
	v_pk_fma_f32 v[32:33], v[32:33], v[32:33], v[34:35]
	v_mov_b32_e32 v72, v3
	v_pk_fma_f32 v[32:33], v[70:71], v[70:71], v[32:33]
	s_nop 0
	v_pk_fma_f32 v[32:33], v[72:73], v[72:73], v[32:33]
	s_nop 0
	v_add_f32_e32 v33, v33, v74
	v_add_f32_e32 v32, v32, v33
	ds_bpermute_b32 v33, v75, v32
	s_waitcnt lgkmcnt(0)
	v_add_f32_e32 v32, v32, v33
	ds_bpermute_b32 v33, v94, v32
	s_waitcnt lgkmcnt(0)
	v_add_f32_e32 v32, v32, v33
	ds_bpermute_b32 v33, v95, v32
	s_waitcnt lgkmcnt(0)
	v_add_f32_e32 v32, v32, v33
	ds_bpermute_b32 v33, v96, v32
	s_waitcnt lgkmcnt(0)
	v_add_f32_e32 v32, v32, v33
	ds_bpermute_b32 v33, v97, v32
	s_waitcnt lgkmcnt(0)
	v_add_f32_e32 v32, v32, v33
	ds_bpermute_b32 v33, v98, v32
	s_waitcnt lgkmcnt(0)
	v_add_f32_e32 v32, v32, v33
	v_fmamk_f32 v32, v32, 0x3a000000, v184
	v_mul_f32_e32 v33, 0x4b800000, v32
	v_cmp_gt_f32_e32 vcc, s92, v32
	s_nop 1
	v_cndmask_b32_e32 v32, v32, v33, vcc
	v_rsq_f32_e32 v32, v32
	s_nop 0
	v_mul_f32_e32 v33, 0x45800000, v32
	v_cndmask_b32_e32 v32, v32, v33, vcc
	v_pk_mul_f32 v[4:5], v[4:5], v[32:33] op_sel_hi:[1,0]
	v_pk_mul_f32 v[6:7], v[6:7], v[32:33] op_sel_hi:[1,0]
	v_pk_mul_f32 v[16:17], v[16:17], v[32:33] op_sel_hi:[1,0]
	v_pk_mul_f32 v[18:19], v[18:19], v[32:33] op_sel_hi:[1,0]
	v_add_co_u32_e32 v34, vcc, s0, v62
	v_pk_mul_f32 v[8:9], v[8:9], v[32:33] op_sel_hi:[1,0]
	s_nop 0
	v_addc_co_u32_e32 v35, vcc, -1, v63, vcc
	v_pk_mul_f32 v[10:11], v[10:11], v[32:33] op_sel_hi:[1,0]
	v_pk_mul_f32 v[0:1], v[0:1], v[32:33] op_sel_hi:[1,0]
	v_pk_mul_f32 v[2:3], v[2:3], v[32:33] op_sel_hi:[1,0]
	v_lshl_add_u64 v[62:63], v[62:63], 0, s[8:9]
	v_pk_mul_f32 v[6:7], v[68:69], v[6:7]
	v_pk_mul_f32 v[4:5], v[66:67], v[4:5]
	s_nop 0
	v_cvt_pk_bf16_f32 v4, v4, v5
	v_cvt_pk_bf16_f32 v5, v6, v7
	global_store_dwordx2 v[76:77], v[4:5], off
	v_mov_b32_e32 v6, v154
	v_mov_b32_e32 v7, v155
	v_mov_b32_e32 v4, v152
	v_mov_b32_e32 v5, v153
	v_pk_mul_f32 v[6:7], v[6:7], v[18:19]
	v_pk_mul_f32 v[4:5], v[4:5], v[16:17]
	s_nop 0
	v_cvt_pk_bf16_f32 v4, v4, v5
	v_cvt_pk_bf16_f32 v5, v6, v7
	global_store_dwordx2 v[34:35], v[4:5], off offset:-3584
	v_mov_b32_e32 v6, v158
	v_mov_b32_e32 v7, v159
	v_mov_b32_e32 v4, v156
	v_mov_b32_e32 v5, v157
	v_pk_mul_f32 v[6:7], v[6:7], v[10:11]
	v_pk_mul_f32 v[4:5], v[4:5], v[8:9]
	v_pk_mul_f32 v[8:9], v[12:13], v[32:33] op_sel_hi:[1,0]
	v_cvt_pk_bf16_f32 v4, v4, v5
	v_cvt_pk_bf16_f32 v5, v6, v7
	global_store_dwordx2 v[34:35], v[4:5], off offset:-3072
	v_mov_b32_e32 v6, v162
	v_mov_b32_e32 v7, v163
	v_mov_b32_e32 v4, v160
	v_mov_b32_e32 v5, v161
	v_pk_mul_f32 v[10:11], v[14:15], v[32:33] op_sel_hi:[1,0]
	v_pk_mul_f32 v[4:5], v[4:5], v[8:9]
	v_pk_mul_f32 v[6:7], v[6:7], v[10:11]
	v_cvt_pk_bf16_f32 v4, v4, v5
	v_cvt_pk_bf16_f32 v5, v6, v7
	global_store_dwordx2 v[34:35], v[4:5], off offset:-2560
	v_mov_b32_e32 v6, v166
	v_mov_b32_e32 v7, v167
	v_mov_b32_e32 v4, v164
	v_mov_b32_e32 v5, v165
	v_pk_mul_f32 v[8:9], v[20:21], v[32:33] op_sel_hi:[1,0]
	v_pk_mul_f32 v[10:11], v[22:23], v[32:33] op_sel_hi:[1,0]
	v_pk_mul_f32 v[4:5], v[4:5], v[8:9]
	v_pk_mul_f32 v[6:7], v[6:7], v[10:11]
	v_cvt_pk_bf16_f32 v4, v4, v5
	v_cvt_pk_bf16_f32 v5, v6, v7
	global_store_dwordx2 v[34:35], v[4:5], off offset:-2048
	v_mov_b32_e32 v6, v170
	v_mov_b32_e32 v7, v171
	v_mov_b32_e32 v4, v168
	v_mov_b32_e32 v5, v169
	v_pk_mul_f32 v[8:9], v[24:25], v[32:33] op_sel_hi:[1,0]
	v_pk_mul_f32 v[10:11], v[26:27], v[32:33] op_sel_hi:[1,0]
	v_pk_mul_f32 v[4:5], v[4:5], v[8:9]
	v_pk_mul_f32 v[6:7], v[6:7], v[10:11]
	v_cvt_pk_bf16_f32 v4, v4, v5
	v_cvt_pk_bf16_f32 v5, v6, v7
	global_store_dwordx2 v[34:35], v[4:5], off offset:-1536
	v_mov_b32_e32 v6, v174
	v_mov_b32_e32 v7, v175
	v_mov_b32_e32 v4, v172
	v_mov_b32_e32 v5, v173
	v_pk_mul_f32 v[8:9], v[28:29], v[32:33] op_sel_hi:[1,0]
	v_pk_mul_f32 v[10:11], v[30:31], v[32:33] op_sel_hi:[1,0]
	v_pk_mul_f32 v[4:5], v[4:5], v[8:9]
	v_pk_mul_f32 v[6:7], v[6:7], v[10:11]
	v_cvt_pk_bf16_f32 v4, v4, v5
	v_cvt_pk_bf16_f32 v5, v6, v7
	global_store_dwordx2 v[34:35], v[4:5], off offset:-1024
	v_mov_b32_e32 v6, v178
	v_mov_b32_e32 v7, v179
	v_mov_b32_e32 v4, v176
	v_mov_b32_e32 v5, v177
	v_pk_mul_f32 v[2:3], v[6:7], v[2:3]
	v_pk_mul_f32 v[0:1], v[4:5], v[0:1]
	s_nop 0
	v_cvt_pk_bf16_f32 v0, v0, v1
	v_cvt_pk_bf16_f32 v1, v2, v3
	global_store_dwordx2 v[34:35], v[0:1], off offset:-512
	s_cbranch_scc1 .LBB0_415

.LBB0_423:
	s_lshl_b32 s0, s34, 3
	v_readlane_b32 s2, v255, 18
	s_add_i32 s4, s2, s0
	s_cmpk_gt_i32 s4, 0x3fff
	s_cbranch_scc1 .LBB0_426
	s_waitcnt vmcnt(0)
	v_and_b32_e32 v0, 64, v185
	v_add_u32_e32 v0, 64, v0
	v_xor_b32_e32 v1, 32, v185
	v_xor_b32_e32 v2, 16, v185
	v_cmp_lt_i32_e32 vcc, v1, v0
	s_waitcnt lgkmcnt(0)
	v_xor_b32_e32 v3, 8, v185
	v_xor_b32_e32 v4, 4, v185
	v_cndmask_b32_e32 v1, v185, v1, vcc
	v_cmp_lt_i32_e32 vcc, v2, v0
	v_lshlrev_b32_e32 v18, 2, v1
	v_xor_b32_e32 v5, 2, v185
	v_cndmask_b32_e32 v1, v185, v2, vcc
	v_cmp_lt_i32_e32 vcc, v3, v0
	v_lshlrev_b32_e32 v19, 2, v1
	v_xor_b32_e32 v6, 1, v185
	v_cndmask_b32_e32 v1, v185, v3, vcc
	v_cmp_lt_i32_e32 vcc, v4, v0
	v_lshlrev_b32_e32 v20, 2, v1
	v_readlane_b32 s2, v254, 1
	v_cndmask_b32_e32 v1, v185, v4, vcc
	v_cmp_lt_i32_e32 vcc, v5, v0
	v_lshlrev_b32_e32 v21, 2, v1
	v_lshlrev_b32_e32 v64, 4, v189
	v_cndmask_b32_e32 v1, v185, v5, vcc
	v_cmp_lt_i32_e32 vcc, v6, v0
	v_readlane_b32 s3, v254, 2
	s_ashr_i32 s5, s4, 31
	v_cndmask_b32_e32 v0, v185, v6, vcc
	v_lshl_add_u64 v[6:7], s[2:3], 0, v[64:65]
	v_readlane_b32 s2, v254, 3
	v_readlane_b32 s3, v254, 4
	s_lshl_b32 s6, s42, 3
	v_lshlrev_b32_e32 v22, 2, v1
	v_lshl_add_u64 v[8:9], s[2:3], 0, v[64:65]
	v_readlane_b32 s2, v254, 5
	v_readlane_b32 s3, v254, 6
	v_lshlrev_b32_e32 v23, 2, v0
	v_readlane_b32 s8, v252, 9
	v_lshl_add_u64 v[10:11], s[2:3], 0, v[64:65]
	v_readlane_b32 s2, v254, 7
	v_readlane_b32 s3, v254, 8
	v_lshlrev_b32_e32 v0, 3, v189
	v_mov_b32_e32 v1, v65
	v_lshl_add_u64 v[12:13], s[2:3], 0, v[64:65]
	s_lshl_b64 s[2:3], s[4:5], 12
	s_add_u32 s2, s70, s2
	s_addc_u32 s3, s71, s3
	v_readlane_b32 s9, v252, 10
	v_lshl_add_u64 v[0:1], s[2:3], 0, v[0:1]
	s_mov_b64 s[2:3], 0x5100000
	s_ashr_i32 s7, s6, 31
	v_lshl_add_u64 v[14:15], v[0:1], 0, s[2:3]
	s_lshl_b64 s[8:9], s[6:7], 12
	s_lshl_b64 s[2:3], s[4:5], 13
	v_readlane_b32 s0, v254, 51
	s_add_u32 s2, s0, s2
	v_readlane_b32 s0, v254, 52
	v_readlane_b32 s10, v252, 11
	v_readlane_b32 s11, v252, 12
	s_addc_u32 s3, s0, s3
	v_lshl_add_u64 v[16:17], s[2:3], 0, v[64:65]
	v_lshl_add_u64 v[4:5], s[10:11], 0, v[64:65]
	s_lshl_b64 s[10:11], s[6:7], 13
	v_readlane_b32 s12, v252, 13
	v_readlane_b32 s13, v252, 14
	v_readlane_b32 s14, v252, 15
	v_readlane_b32 s15, v252, 16
	v_readlane_b32 s16, v252, 17
	v_readlane_b32 s17, v252, 18
	v_readlane_b32 s18, v252, 19
	v_readlane_b32 s19, v252, 20
	v_readlane_b32 s20, v252, 21
	v_readlane_b32 s21, v252, 22
	v_readlane_b32 s22, v252, 23
	v_readlane_b32 s23, v252, 24
	global_load_dwordx4 v[80:83], v[4:5], off
	global_load_dwordx4 v[84:87], v[4:5], off offset:1024
	global_load_dwordx4 v[88:91], v[4:5], off offset:2048
	global_load_dwordx4 v[92:95], v[4:5], off offset:3072
	global_load_dwordx4 v[96:99], v[6:7], off
	global_load_dwordx4 v[100:103], v[8:9], off
	global_load_dwordx4 v[104:107], v[10:11], off
	global_load_dwordx4 v[108:111], v[12:13], off
	s_waitcnt vmcnt(0)
.LBB0_425:
	global_load_dwordx4 v[24:27], v[16:17], off offset:-4096 nt
	global_load_dwordx4 v[28:31], v[16:17], off offset:-3072 nt
	global_load_dwordx4 v[32:35], v[16:17], off offset:-2048 nt
	global_load_dwordx4 v[36:39], v[16:17], off offset:-1024 nt
	global_load_dwordx4 v[40:43], v[16:17], off nt
	global_load_dwordx4 v[44:47], v[16:17], off offset:1024 nt
	global_load_dwordx4 v[48:51], v[16:17], off offset:2048 nt
	global_load_dwordx4 v[0:3], v[16:17], off offset:3072 nt
	v_mov_b32_e32 v54, v82
	v_mov_b32_e32 v55, v83
	v_mov_b32_e32 v52, v80
	v_mov_b32_e32 v53, v81
	s_add_i32 s4, s4, s6
	v_lshl_add_u64 v[16:17], v[16:17], 0, s[10:11]
	s_cmpk_gt_i32 s4, 0x3fff
	s_waitcnt vmcnt(7)
	v_mul_f32_e32 v64, v25, v25
	s_waitcnt vmcnt(6)
	v_mul_f32_e32 v74, v29, v29
	s_waitcnt vmcnt(5)
	v_mul_f32_e32 v75, v33, v33
	v_fmac_f32_e32 v64, v24, v24
	s_waitcnt vmcnt(3)
	v_mov_b32_e32 v58, v41
	s_waitcnt vmcnt(2)
	v_mov_b32_e32 v59, v45
	v_fmac_f32_e32 v74, v28, v28
	v_mul_f32_e32 v76, v37, v37
	v_mov_b32_e32 v56, v40
	v_mov_b32_e32 v57, v44
	v_fmac_f32_e32 v75, v32, v32
	v_pk_mul_f32 v[58:59], v[58:59], v[58:59]
	v_fmac_f32_e32 v64, v26, v26
	v_fmac_f32_e32 v74, v30, v30
	v_mov_b32_e32 v60, v42
	v_mov_b32_e32 v61, v46
	v_fmac_f32_e32 v76, v36, v36
	v_fmac_f32_e32 v75, v34, v34
	v_pk_fma_f32 v[56:57], v[56:57], v[56:57], v[58:59]
	v_fmac_f32_e32 v64, v27, v27
	v_fmac_f32_e32 v74, v31, v31
	s_waitcnt vmcnt(1)
	v_mov_b32_e32 v68, v49
	s_waitcnt vmcnt(0)
	v_mov_b32_e32 v69, v1
	v_fmac_f32_e32 v76, v38, v38
	v_fmac_f32_e32 v75, v35, v35
	v_pk_fma_f32 v[56:57], v[60:61], v[60:61], v[56:57]
	v_add_f32_e32 v60, v64, v74
	v_mov_b32_e32 v62, v43
	v_mov_b32_e32 v63, v47
	v_mov_b32_e32 v66, v48
	v_mov_b32_e32 v67, v0
	v_pk_mul_f32 v[68:69], v[68:69], v[68:69]
	v_fmac_f32_e32 v76, v39, v39
	v_add_f32_e32 v60, v60, v75
	v_mov_b32_e32 v70, v50
	v_mov_b32_e32 v71, v2
	v_pk_fma_f32 v[58:59], v[66:67], v[66:67], v[68:69]
	v_pk_fma_f32 v[56:57], v[62:63], v[62:63], v[56:57]
	v_add_f32_e32 v60, v60, v76
	v_mov_b32_e32 v72, v51
	v_mov_b32_e32 v73, v3
	v_pk_fma_f32 v[58:59], v[70:71], v[70:71], v[58:59]
	v_add_f32_e32 v56, v60, v56
	v_pk_fma_f32 v[58:59], v[72:73], v[72:73], v[58:59]
	v_add_f32_e32 v56, v56, v57
	v_add_f32_e32 v56, v56, v58
	v_add_f32_e32 v56, v56, v59
	ds_bpermute_b32 v57, v18, v56
	s_waitcnt lgkmcnt(0)
	v_add_f32_e32 v56, v56, v57
	ds_bpermute_b32 v57, v19, v56
	s_waitcnt lgkmcnt(0)
	v_add_f32_e32 v56, v56, v57
	ds_bpermute_b32 v57, v20, v56
	s_waitcnt lgkmcnt(0)
	v_add_f32_e32 v56, v56, v57
	ds_bpermute_b32 v57, v21, v56
	s_waitcnt lgkmcnt(0)
	v_add_f32_e32 v56, v56, v57
	ds_bpermute_b32 v57, v22, v56
	s_waitcnt lgkmcnt(0)
	v_add_f32_e32 v56, v56, v57
	ds_bpermute_b32 v57, v23, v56
	s_waitcnt lgkmcnt(0)
	v_add_f32_e32 v56, v56, v57
	v_fmamk_f32 v56, v56, 0x3a000000, v184
	v_mul_f32_e32 v57, 0x4b800000, v56
	v_cmp_gt_f32_e32 vcc, s92, v56
	s_nop 1
	v_cndmask_b32_e32 v56, v56, v57, vcc
	v_rsq_f32_e32 v56, v56
	s_nop 0
	v_mul_f32_e32 v57, 0x45800000, v56
	v_cndmask_b32_e32 v56, v56, v57, vcc
	v_pk_mul_f32 v[24:25], v[24:25], v[56:57] op_sel_hi:[1,0]
	v_pk_mul_f32 v[26:27], v[26:27], v[56:57] op_sel_hi:[1,0]
	v_pk_mul_f32 v[24:25], v[52:53], v[24:25]
	v_pk_mul_f32 v[26:27], v[54:55], v[26:27]
	v_cvt_pk_bf16_f32 v24, v24, v25
	v_cvt_pk_bf16_f32 v25, v26, v27
	global_store_dwordx2 v[14:15], v[24:25], off
	v_mov_b32_e32 v26, v86
	v_mov_b32_e32 v27, v87
	v_mov_b32_e32 v24, v84
	v_mov_b32_e32 v25, v85
	v_pk_mul_f32 v[28:29], v[28:29], v[56:57] op_sel_hi:[1,0]
	v_pk_mul_f32 v[30:31], v[30:31], v[56:57] op_sel_hi:[1,0]
	v_pk_mul_f32 v[0:1], v[0:1], v[56:57] op_sel_hi:[1,0]
	v_pk_mul_f32 v[2:3], v[2:3], v[56:57] op_sel_hi:[1,0]
	v_pk_mul_f32 v[26:27], v[26:27], v[30:31]
	v_pk_mul_f32 v[24:25], v[24:25], v[28:29]
	v_pk_mul_f32 v[28:29], v[32:33], v[56:57] op_sel_hi:[1,0]
	v_cvt_pk_bf16_f32 v24, v24, v25
	v_cvt_pk_bf16_f32 v25, v26, v27
	global_store_dwordx2 v[14:15], v[24:25], off offset:512
	v_mov_b32_e32 v26, v90
	v_mov_b32_e32 v27, v91
	v_mov_b32_e32 v24, v88
	v_mov_b32_e32 v25, v89
	v_pk_mul_f32 v[30:31], v[34:35], v[56:57] op_sel_hi:[1,0]
	v_pk_mul_f32 v[24:25], v[24:25], v[28:29]
	v_pk_mul_f32 v[26:27], v[26:27], v[30:31]
	v_cvt_pk_bf16_f32 v24, v24, v25
	v_cvt_pk_bf16_f32 v25, v26, v27
	global_store_dwordx2 v[14:15], v[24:25], off offset:1024
	v_mov_b32_e32 v26, v94
	v_mov_b32_e32 v27, v95
	v_mov_b32_e32 v24, v92
	v_mov_b32_e32 v25, v93
	v_pk_mul_f32 v[28:29], v[36:37], v[56:57] op_sel_hi:[1,0]
	v_pk_mul_f32 v[30:31], v[38:39], v[56:57] op_sel_hi:[1,0]
	v_pk_mul_f32 v[24:25], v[24:25], v[28:29]
	v_pk_mul_f32 v[26:27], v[26:27], v[30:31]
	v_cvt_pk_bf16_f32 v24, v24, v25
	v_cvt_pk_bf16_f32 v25, v26, v27
	global_store_dwordx2 v[14:15], v[24:25], off offset:1536
	v_mov_b32_e32 v26, v98
	v_mov_b32_e32 v27, v99
	v_mov_b32_e32 v24, v96
	v_mov_b32_e32 v25, v97
	v_pk_mul_f32 v[28:29], v[40:41], v[56:57] op_sel_hi:[1,0]
	v_pk_mul_f32 v[30:31], v[42:43], v[56:57] op_sel_hi:[1,0]
	v_pk_mul_f32 v[24:25], v[24:25], v[28:29]
	v_pk_mul_f32 v[26:27], v[26:27], v[30:31]
	v_cvt_pk_bf16_f32 v24, v24, v25
	v_cvt_pk_bf16_f32 v25, v26, v27
	global_store_dwordx2 v[14:15], v[24:25], off offset:2048
	v_mov_b32_e32 v26, v102
	v_mov_b32_e32 v27, v103
	v_mov_b32_e32 v24, v100
	v_mov_b32_e32 v25, v101
	v_pk_mul_f32 v[28:29], v[44:45], v[56:57] op_sel_hi:[1,0]
	v_pk_mul_f32 v[30:31], v[46:47], v[56:57] op_sel_hi:[1,0]
	v_pk_mul_f32 v[24:25], v[24:25], v[28:29]
	v_pk_mul_f32 v[26:27], v[26:27], v[30:31]
	v_cvt_pk_bf16_f32 v24, v24, v25
	v_cvt_pk_bf16_f32 v25, v26, v27
	global_store_dwordx2 v[14:15], v[24:25], off offset:2560
	v_mov_b32_e32 v26, v106
	v_mov_b32_e32 v27, v107
	v_mov_b32_e32 v24, v104
	v_mov_b32_e32 v25, v105
	v_pk_mul_f32 v[28:29], v[48:49], v[56:57] op_sel_hi:[1,0]
	v_pk_mul_f32 v[30:31], v[50:51], v[56:57] op_sel_hi:[1,0]
	v_pk_mul_f32 v[24:25], v[24:25], v[28:29]
	v_pk_mul_f32 v[26:27], v[26:27], v[30:31]
	v_cvt_pk_bf16_f32 v24, v24, v25
	v_cvt_pk_bf16_f32 v25, v26, v27
	global_store_dwordx2 v[14:15], v[24:25], off offset:3072
	v_mov_b32_e32 v26, v110
	v_mov_b32_e32 v27, v111
	v_mov_b32_e32 v24, v108
	v_mov_b32_e32 v25, v109
	v_pk_mul_f32 v[2:3], v[26:27], v[2:3]
	v_pk_mul_f32 v[0:1], v[24:25], v[0:1]
	s_nop 0
	v_cvt_pk_bf16_f32 v0, v0, v1
	v_cvt_pk_bf16_f32 v1, v2, v3
	global_store_dwordx2 v[14:15], v[0:1], off offset:3584
	v_lshl_add_u64 v[14:15], v[14:15], 0, s[8:9]
	s_cbranch_scc0 .LBB0_425

.LBB0_464:
	s_and_b64 vcc, exec, s[4:5]
	s_cbranch_vccz .LBB0_10
	s_lshl_b32 s0, s34, 3
	v_readlane_b32 s2, v255, 18
	s_add_i32 s4, s2, s0
	s_cmpk_gt_i32 s4, 0x3fff
	s_cbranch_scc1 .LBB0_10
	v_readlane_b32 s2, v254, 9
	v_lshlrev_b32_e32 v64, 4, v189
	v_readlane_b32 s3, v254, 10
	s_waitcnt vmcnt(0)
	v_and_b32_e32 v0, 64, v185
	v_add_u32_e32 v0, 64, v0
	v_lshl_add_u64 v[12:13], s[2:3], 0, v[64:65]
	v_readlane_b32 s2, v254, 11
	v_readlane_b32 s3, v254, 12
	v_xor_b32_e32 v1, 32, v185
	v_cmp_lt_i32_e32 vcc, v1, v0
	v_lshl_add_u64 v[14:15], s[2:3], 0, v[64:65]
	v_readlane_b32 s2, v254, 13
	v_readlane_b32 s3, v254, 14
	v_cndmask_b32_e32 v1, v185, v1, vcc
	v_lshlrev_b32_e32 v70, 2, v1
	v_lshl_add_u64 v[16:17], s[2:3], 0, v[64:65]
	v_readlane_b32 s2, v254, 15
	v_xor_b32_e32 v1, 16, v185
	v_readlane_b32 s3, v254, 16
	v_cmp_lt_i32_e32 vcc, v1, v0
	s_ashr_i32 s5, s4, 31
	v_lshl_add_u64 v[18:19], s[2:3], 0, v[64:65]
	v_readlane_b32 s2, v254, 17
	v_cndmask_b32_e32 v1, v185, v1, vcc
	v_readlane_b32 s3, v254, 18
	v_lshlrev_b32_e32 v71, 2, v1
	v_xor_b32_e32 v1, 8, v185
	v_lshl_add_u64 v[20:21], s[2:3], 0, v[64:65]
	v_readlane_b32 s2, v254, 19
	v_cmp_lt_i32_e32 vcc, v1, v0
	v_readlane_b32 s3, v254, 20
	s_waitcnt lgkmcnt(0)
	s_lshl_b32 s6, s42, 3
	v_cndmask_b32_e32 v1, v185, v1, vcc
	v_lshl_add_u64 v[22:23], s[2:3], 0, v[64:65]
	v_readlane_b32 s2, v254, 21
	v_lshlrev_b32_e32 v72, 2, v1
	v_xor_b32_e32 v1, 4, v185
	v_readlane_b32 s3, v254, 22
	v_cmp_lt_i32_e32 vcc, v1, v0
	v_readlane_b32 s0, v254, 53
	v_lshl_add_u64 v[24:25], s[2:3], 0, v[64:65]
	v_readlane_b32 s2, v254, 23
	v_cndmask_b32_e32 v1, v185, v1, vcc
	v_readlane_b32 s3, v254, 24
	v_lshlrev_b32_e32 v73, 2, v1
	v_xor_b32_e32 v1, 2, v185
	v_lshl_add_u64 v[26:27], s[2:3], 0, v[64:65]
	s_lshl_b64 s[2:3], s[4:5], 13
	v_cmp_lt_i32_e32 vcc, v1, v0
	s_add_u32 s2, s0, s2
	v_readlane_b32 s0, v254, 54
	v_cndmask_b32_e32 v1, v185, v1, vcc
	s_addc_u32 s3, s0, s3
	s_ashr_i32 s7, s6, 31
	v_lshlrev_b32_e32 v74, 2, v1
	v_xor_b32_e32 v1, 1, v185
	v_lshl_add_u64 v[28:29], s[2:3], 0, v[64:65]
	s_lshl_b64 s[8:9], s[6:7], 13
	s_lshl_b64 s[2:3], s[4:5], 12
	v_cmp_lt_i32_e32 vcc, v1, v0
	s_add_u32 s2, s70, s2
	v_lshlrev_b32_e32 v64, 3, v189
	v_cndmask_b32_e32 v0, v185, v1, vcc
	s_addc_u32 s3, s71, s3
	v_lshlrev_b32_e32 v75, 2, v0
	v_lshl_add_u64 v[0:1], s[2:3], 0, v[64:65]
	s_mov_b64 s[2:3], 0x29100000
	v_lshl_add_u64 v[30:31], v[0:1], 0, s[2:3]
	s_lshl_b64 s[10:11], s[6:7], 12
	global_load_dwordx4 v[80:83], v[12:13], off
	global_load_dwordx4 v[84:87], v[14:15], off
	global_load_dwordx4 v[88:91], v[16:17], off
	global_load_dwordx4 v[92:95], v[18:19], off
	global_load_dwordx4 v[96:99], v[20:21], off
	global_load_dwordx4 v[100:103], v[22:23], off
	global_load_dwordx4 v[104:107], v[24:25], off
	global_load_dwordx4 v[108:111], v[26:27], off
	s_waitcnt vmcnt(0)
.LBB0_467:
	global_load_dwordx2 v[32:33], v[30:31], off nt
	global_load_dwordx2 v[34:35], v[30:31], off offset:512 nt
	global_load_dwordx2 v[36:37], v[30:31], off offset:1024 nt
	global_load_dwordx2 v[38:39], v[30:31], off offset:1536 nt
	global_load_dwordx2 v[40:41], v[30:31], off offset:2560 nt
	global_load_dwordx2 v[50:51], v[30:31], off offset:3072 nt
	global_load_dwordx2 v[54:55], v[30:31], off offset:2048 nt
	global_load_dwordx2 v[52:53], v[30:31], off offset:3584 nt
	global_load_dwordx4 v[8:11], v[28:29], off offset:-4096 nt
	global_load_dwordx4 v[4:7], v[28:29], off offset:-3072 nt
	global_load_dwordx4 v[112:115], v[28:29], off offset:-2048 nt
	global_load_dwordx4 v[116:119], v[28:29], off offset:-1024 nt
	global_load_dwordx4 v[120:123], v[28:29], off nt
	global_load_dwordx4 v[124:127], v[28:29], off offset:1024 nt
	global_load_dwordx4 v[128:131], v[28:29], off offset:2048 nt
	global_load_dwordx4 v[132:135], v[28:29], off offset:3072 nt
	s_add_i32 s4, s4, s6
	v_lshl_add_u64 v[30:31], v[30:31], 0, s[10:11]
	s_cmpk_gt_i32 s4, 0x3fff
	s_waitcnt vmcnt(15)
	v_and_b32_e32 v77, 0xffff0000, v32
	s_waitcnt vmcnt(14)
	v_and_b32_e32 v67, 0xffff0000, v34
	v_lshlrev_b32_e32 v76, 16, v32
	v_lshlrev_b32_e32 v78, 16, v33
	v_and_b32_e32 v79, 0xffff0000, v33
	v_lshlrev_b32_e32 v66, 16, v34
	v_lshlrev_b32_e32 v68, 16, v35
	v_and_b32_e32 v69, 0xffff0000, v35
	s_waitcnt vmcnt(13)
	v_and_b32_e32 v61, 0xffff0000, v36
	v_lshlrev_b32_e32 v62, 16, v37
	v_and_b32_e32 v63, 0xffff0000, v37
	s_waitcnt vmcnt(12)
	v_lshlrev_b32_e32 v58, 16, v39
	v_and_b32_e32 v59, 0xffff0000, v39
	s_waitcnt vmcnt(8)
	v_lshlrev_b32_e32 v35, 16, v52
	v_and_b32_e32 v33, 0xffff0000, v52
	v_lshlrev_b32_e32 v37, 16, v53
	v_and_b32_e32 v39, 0xffff0000, v53
	v_mul_f32_e32 v52, v77, v77
	v_mul_f32_e32 v53, v67, v67
	v_lshlrev_b32_e32 v60, 16, v36
	v_and_b32_e32 v57, 0xffff0000, v38
	v_lshlrev_b32_e32 v44, 16, v54
	v_and_b32_e32 v42, 0xffff0000, v54
	v_mul_f32_e32 v54, v61, v61
	v_fmac_f32_e32 v52, v76, v76
	v_fmac_f32_e32 v53, v66, v66
	v_lshlrev_b32_e32 v56, 16, v38
	v_and_b32_e32 v43, 0xffff0000, v40
	v_lshlrev_b32_e32 v46, 16, v55
	v_and_b32_e32 v48, 0xffff0000, v55
	v_mul_f32_e32 v55, v57, v57
	v_fmac_f32_e32 v54, v60, v60
	v_fmac_f32_e32 v52, v78, v78
	v_fmac_f32_e32 v53, v68, v68
	v_lshlrev_b32_e32 v45, 16, v40
	v_lshlrev_b32_e32 v47, 16, v41
	v_and_b32_e32 v49, 0xffff0000, v41
	v_pk_mul_f32 v[40:41], v[42:43], v[42:43]
	v_fmac_f32_e32 v55, v56, v56
	v_fmac_f32_e32 v54, v62, v62
	v_fmac_f32_e32 v52, v79, v79
	v_fmac_f32_e32 v53, v69, v69
	v_and_b32_e32 v32, 0xffff0000, v50
	v_pk_fma_f32 v[40:41], v[44:45], v[44:45], v[40:41]
	v_fmac_f32_e32 v55, v58, v58
	v_fmac_f32_e32 v54, v63, v63
	v_add_f32_e32 v52, v52, v53
	v_lshlrev_b32_e32 v34, 16, v50
	v_lshlrev_b32_e32 v36, 16, v51
	v_and_b32_e32 v38, 0xffff0000, v51
	v_pk_mul_f32 v[50:51], v[32:33], v[32:33]
	v_pk_fma_f32 v[40:41], v[46:47], v[46:47], v[40:41]
	v_fmac_f32_e32 v55, v59, v59
	v_add_f32_e32 v52, v52, v54
	v_pk_fma_f32 v[50:51], v[34:35], v[34:35], v[50:51]
	v_pk_fma_f32 v[40:41], v[48:49], v[48:49], v[40:41]
	v_add_f32_e32 v52, v52, v55
	v_pk_fma_f32 v[50:51], v[36:37], v[36:37], v[50:51]
	v_add_f32_e32 v40, v52, v40
	v_pk_fma_f32 v[50:51], v[38:39], v[38:39], v[50:51]
	v_add_f32_e32 v40, v40, v41
	v_add_f32_e32 v40, v40, v50
	v_add_f32_e32 v40, v40, v51
	ds_bpermute_b32 v41, v70, v40
	s_waitcnt lgkmcnt(0)
	v_add_f32_e32 v40, v40, v41
	ds_bpermute_b32 v41, v71, v40
	s_waitcnt lgkmcnt(0)
	v_add_f32_e32 v40, v40, v41
	ds_bpermute_b32 v41, v72, v40
	s_waitcnt lgkmcnt(0)
	v_add_f32_e32 v40, v40, v41
	ds_bpermute_b32 v41, v73, v40
	s_waitcnt lgkmcnt(0)
	v_add_f32_e32 v40, v40, v41
	ds_bpermute_b32 v41, v74, v40
	s_waitcnt lgkmcnt(0)
	v_add_f32_e32 v40, v40, v41
	ds_bpermute_b32 v41, v75, v40
	s_waitcnt lgkmcnt(0)
	v_add_f32_e32 v40, v40, v41
	v_fmamk_f32 v40, v40, 0x3a000000, v184
	v_mul_f32_e32 v41, 0x4b800000, v40
	v_cmp_gt_f32_e32 vcc, s92, v40
	s_nop 1
	v_cndmask_b32_e32 v40, v40, v41, vcc
	v_rsq_f32_e32 v40, v40
	s_nop 0
	v_mul_f32_e32 v41, 0x45800000, v40
	v_cndmask_b32_e32 v40, v40, v41, vcc
	v_pk_mul_f32 v[50:51], v[76:77], v[40:41] op_sel_hi:[1,0]
	v_pk_mul_f32 v[52:53], v[78:79], v[40:41] op_sel_hi:[1,0]
	s_waitcnt vmcnt(7)
	v_pk_fma_f32 v[0:1], v[80:81], v[50:51], v[8:9]
	v_pk_fma_f32 v[2:3], v[82:83], v[52:53], v[10:11]
	global_store_dwordx4 v[28:29], v[0:3], off offset:-4096 nt
	s_nop 1
	v_pk_mul_f32 v[50:51], v[68:69], v[40:41] op_sel_hi:[1,0]
	v_pk_mul_f32 v[52:53], v[66:67], v[40:41] op_sel_hi:[1,0]
	s_waitcnt vmcnt(7)
	v_pk_fma_f32 v[2:3], v[86:87], v[50:51], v[6:7]
	v_pk_fma_f32 v[0:1], v[84:85], v[52:53], v[4:5]
	global_store_dwordx4 v[28:29], v[0:3], off offset:-3072 nt
	s_nop 1
	v_pk_mul_f32 v[50:51], v[62:63], v[40:41] op_sel_hi:[1,0]
	v_pk_mul_f32 v[52:53], v[60:61], v[40:41] op_sel_hi:[1,0]
	s_waitcnt vmcnt(7)
	v_pk_fma_f32 v[2:3], v[90:91], v[50:51], v[114:115]
	v_pk_fma_f32 v[0:1], v[88:89], v[52:53], v[112:113]
	global_store_dwordx4 v[28:29], v[0:3], off offset:-2048 nt
	s_nop 1
	v_pk_mul_f32 v[50:51], v[58:59], v[40:41] op_sel_hi:[1,0]
	v_pk_mul_f32 v[52:53], v[56:57], v[40:41] op_sel_hi:[1,0]
	s_waitcnt vmcnt(7)
	v_pk_fma_f32 v[2:3], v[94:95], v[50:51], v[118:119]
	v_pk_fma_f32 v[0:1], v[92:93], v[52:53], v[116:117]
	global_store_dwordx4 v[28:29], v[0:3], off offset:-1024 nt
	s_nop 1
	v_mov_b32_e32 v50, v46
	v_mov_b32_e32 v51, v48
	v_mov_b32_e32 v52, v44
	v_mov_b32_e32 v53, v42
	v_pk_mul_f32 v[50:51], v[50:51], v[40:41] op_sel_hi:[1,0]
	v_pk_mul_f32 v[52:53], v[52:53], v[40:41] op_sel_hi:[1,0]
	v_mov_b32_e32 v42, v45
	v_mov_b32_e32 v48, v47
	v_pk_mul_f32 v[44:45], v[48:49], v[40:41] op_sel_hi:[1,0]
	v_pk_mul_f32 v[42:43], v[42:43], v[40:41] op_sel_hi:[1,0]
	s_waitcnt vmcnt(7)
	v_pk_fma_f32 v[0:1], v[96:97], v[52:53], v[120:121]
	v_pk_fma_f32 v[2:3], v[98:99], v[50:51], v[122:123]
	global_store_dwordx4 v[28:29], v[0:3], off nt
	s_nop 1
	s_waitcnt vmcnt(7)
	v_pk_fma_f32 v[0:1], v[100:101], v[42:43], v[124:125]
	v_pk_fma_f32 v[2:3], v[102:103], v[44:45], v[126:127]
	global_store_dwordx4 v[28:29], v[0:3], off offset:1024 nt
	s_nop 1
	v_mov_b32_e32 v42, v36
	v_mov_b32_e32 v43, v38
	v_mov_b32_e32 v44, v34
	v_mov_b32_e32 v45, v32
	v_pk_mul_f32 v[42:43], v[42:43], v[40:41] op_sel_hi:[1,0]
	v_pk_mul_f32 v[44:45], v[44:45], v[40:41] op_sel_hi:[1,0]
	v_mov_b32_e32 v32, v35
	v_mov_b32_e32 v38, v37
	s_waitcnt vmcnt(7)
	v_pk_fma_f32 v[0:1], v[104:105], v[44:45], v[128:129]
	v_pk_fma_f32 v[2:3], v[106:107], v[42:43], v[130:131]
	global_store_dwordx4 v[28:29], v[0:3], off offset:2048 nt
	s_nop 1
	v_pk_mul_f32 v[8:9], v[38:39], v[40:41] op_sel_hi:[1,0]
	v_pk_mul_f32 v[10:11], v[32:33], v[40:41] op_sel_hi:[1,0]
	s_waitcnt vmcnt(7)
	v_pk_fma_f32 v[2:3], v[110:111], v[8:9], v[134:135]
	v_pk_fma_f32 v[0:1], v[108:109], v[10:11], v[132:133]
	global_store_dwordx4 v[28:29], v[0:3], off offset:3072 nt
	s_nop 1
	v_lshl_add_u64 v[28:29], v[28:29], 0, s[8:9]
	s_cbranch_scc0 .LBB0_467
	s_branch .LBB0_10
